# plus: select fast mask-output path, P3 sample items assigned statically (no double draw), removed mid-phase vmcnt(0) in GEMM K-loops, counted vmcnt in P3 attention step A
# speedup vs baseline: 1.1435x; 1.0951x over previous
.LBB0_202:
	v_add_u32_e32 v134, v141, v142
	ds_read_b128 v[170:173], v134
	ds_read_b128 v[174:177], v162 offset:32768
	ds_read_b128 v[178:181], v162 offset:34816
	ds_read_b128 v[182:185], v162 offset:36864
	v_add_u32_e32 v169, v144, v143
	s_add_i32 s23, s23, 2
	s_waitcnt lgkmcnt(0)
	v_mfma_f32_16x16x32_bf16 v[186:189], v[170:173], v[182:185], v[120:123]
	s_nop 2
	ds_read_b128 v[120:123], v162 offset:38912
	v_mfma_f32_16x16x32_bf16 v[124:127], v[170:173], v[174:177], v[124:127]
	v_mfma_f32_16x16x32_bf16 v[116:119], v[170:173], v[178:181], v[116:119]
	s_waitcnt lgkmcnt(0)
	v_mfma_f32_16x16x32_bf16 v[0:3], v[170:173], v[120:123], v[0:3]
	ds_read_b128 v[170:173], v169
	s_waitcnt lgkmcnt(0)
	v_mfma_f32_16x16x32_bf16 v[8:11], v[170:173], v[174:177], v[8:11]
	v_mfma_f32_16x16x32_bf16 v[12:15], v[170:173], v[178:181], v[12:15]
	v_mfma_f32_16x16x32_bf16 v[16:19], v[170:173], v[182:185], v[16:19]
	v_mfma_f32_16x16x32_bf16 v[20:23], v[170:173], v[120:123], v[20:23]
	ds_read_b128 v[170:173], v163
	s_waitcnt lgkmcnt(0)
	v_mfma_f32_16x16x32_bf16 v[24:27], v[170:173], v[174:177], v[24:27]
	v_mfma_f32_16x16x32_bf16 v[28:31], v[170:173], v[178:181], v[28:31]
	v_mfma_f32_16x16x32_bf16 v[32:35], v[170:173], v[182:185], v[32:35]
	v_mfma_f32_16x16x32_bf16 v[36:39], v[170:173], v[120:123], v[36:39]
	ds_read_b128 v[170:173], v164
	s_waitcnt lgkmcnt(0)
	v_mfma_f32_16x16x32_bf16 v[40:43], v[170:173], v[174:177], v[40:43]
	v_mfma_f32_16x16x32_bf16 v[44:47], v[170:173], v[178:181], v[44:47]
	v_mfma_f32_16x16x32_bf16 v[48:51], v[170:173], v[182:185], v[48:51]
	v_mfma_f32_16x16x32_bf16 v[52:55], v[170:173], v[120:123], v[52:55]
	ds_read_b128 v[170:173], v165
	s_waitcnt lgkmcnt(0)
	v_mfma_f32_16x16x32_bf16 v[190:193], v[170:173], v[178:181], v[60:63]
	s_nop 2
	ds_read_b128 v[60:63], v166
	s_waitcnt lgkmcnt(0)
	v_mfma_f32_16x16x32_bf16 v[198:201], v[60:63], v[174:177], v[72:75]
	v_mfma_f32_16x16x32_bf16 v[210:213], v[60:63], v[178:181], v[76:79]
	v_mfma_f32_16x16x32_bf16 v[214:217], v[60:63], v[182:185], v[80:83]
	v_mfma_f32_16x16x32_bf16 v[218:221], v[60:63], v[120:123], v[84:87]
	ds_read_b128 v[60:63], v167
	s_waitcnt lgkmcnt(0)
	v_mfma_f32_16x16x32_bf16 v[222:225], v[60:63], v[174:177], v[88:91]
	v_mfma_f32_16x16x32_bf16 v[226:229], v[60:63], v[178:181], v[92:95]
	v_mfma_f32_16x16x32_bf16 v[230:233], v[60:63], v[182:185], v[96:99]
	v_mfma_f32_16x16x32_bf16 v[234:237], v[60:63], v[120:123], v[100:103]
	ds_read_b128 v[60:63], v168
	v_mfma_f32_16x16x32_bf16 v[56:59], v[170:173], v[174:177], v[56:59]
	v_mfma_f32_16x16x32_bf16 v[194:197], v[170:173], v[182:185], v[64:67]
	v_mfma_f32_16x16x32_bf16 v[170:173], v[170:173], v[120:123], v[68:71]
	s_waitcnt lgkmcnt(0)
	v_mfma_f32_16x16x32_bf16 v[174:177], v[60:63], v[174:177], v[104:107]
	v_mfma_f32_16x16x32_bf16 v[178:181], v[60:63], v[178:181], v[108:111]
	v_mfma_f32_16x16x32_bf16 v[182:185], v[60:63], v[182:185], v[112:115]
	v_mfma_f32_16x16x32_bf16 v[238:241], v[60:63], v[120:123], v[4:7]
	s_nop 2
	ds_read_b128 v[4:7], v134 offset:1024
	ds_read_b128 v[242:245], v162 offset:33792
	ds_read_b128 v[246:249], v162 offset:35840
	ds_read_b128 v[206:209], v162 offset:37888
	s_waitcnt lgkmcnt(1)
	v_mfma_f32_16x16x32_bf16 v[120:123], v[4:7], v[246:249], v[116:119]
	s_waitcnt lgkmcnt(0)
	v_mfma_f32_16x16x32_bf16 v[116:119], v[4:7], v[206:209], v[186:189]
	s_nop 2
	ds_read_b128 v[186:189], v162 offset:39936
	s_waitcnt lgkmcnt(0)
	v_mfma_f32_16x16x32_bf16 v[112:115], v[4:7], v[186:189], v[0:3]
	s_nop 2
	ds_read_b128 v[0:3], v169 offset:1024
	s_waitcnt lgkmcnt(0)
	v_mfma_f32_16x16x32_bf16 v[108:111], v[0:3], v[242:245], v[8:11]
	v_mfma_f32_16x16x32_bf16 v[104:107], v[0:3], v[246:249], v[12:15]
	v_mfma_f32_16x16x32_bf16 v[100:103], v[0:3], v[206:209], v[16:19]
	v_mfma_f32_16x16x32_bf16 v[96:99], v[0:3], v[186:189], v[20:23]
	ds_read_b128 v[0:3], v163 offset:1024
	s_waitcnt lgkmcnt(0)
	v_mfma_f32_16x16x32_bf16 v[92:95], v[0:3], v[242:245], v[24:27]
	v_mfma_f32_16x16x32_bf16 v[88:91], v[0:3], v[246:249], v[28:31]
	v_mfma_f32_16x16x32_bf16 v[84:87], v[0:3], v[206:209], v[32:35]
	v_mfma_f32_16x16x32_bf16 v[80:83], v[0:3], v[186:189], v[36:39]
	ds_read_b128 v[0:3], v164 offset:1024
	s_waitcnt lgkmcnt(0)
	v_mfma_f32_16x16x32_bf16 v[76:79], v[0:3], v[242:245], v[40:43]
	v_mfma_f32_16x16x32_bf16 v[72:75], v[0:3], v[246:249], v[44:47]
	v_mfma_f32_16x16x32_bf16 v[68:71], v[0:3], v[206:209], v[48:51]
	v_mfma_f32_16x16x32_bf16 v[64:67], v[0:3], v[186:189], v[52:55]
	ds_read_b128 v[0:3], v165 offset:1024
	s_waitcnt lgkmcnt(0)
	v_mfma_f32_16x16x32_bf16 v[60:63], v[0:3], v[242:245], v[56:59]
	v_mfma_f32_16x16x32_bf16 v[56:59], v[0:3], v[246:249], v[190:193]
	v_mfma_f32_16x16x32_bf16 v[52:55], v[0:3], v[206:209], v[194:197]
	v_mfma_f32_16x16x32_bf16 v[48:51], v[0:3], v[186:189], v[170:173]
	ds_read_b128 v[0:3], v166 offset:1024
	s_waitcnt lgkmcnt(0)
	v_mfma_f32_16x16x32_bf16 v[44:47], v[0:3], v[242:245], v[198:201]
	v_mfma_f32_16x16x32_bf16 v[40:43], v[0:3], v[246:249], v[210:213]
	v_mfma_f32_16x16x32_bf16 v[36:39], v[0:3], v[206:209], v[214:217]
	v_mfma_f32_16x16x32_bf16 v[32:35], v[0:3], v[186:189], v[218:221]
	ds_read_b128 v[0:3], v167 offset:1024
	s_waitcnt lgkmcnt(0)
	v_mfma_f32_16x16x32_bf16 v[28:31], v[0:3], v[242:245], v[222:225]
	v_mfma_f32_16x16x32_bf16 v[24:27], v[0:3], v[246:249], v[226:229]
	v_mfma_f32_16x16x32_bf16 v[20:23], v[0:3], v[206:209], v[230:233]
	v_mfma_f32_16x16x32_bf16 v[16:19], v[0:3], v[186:189], v[234:237]
	ds_read_b128 v[0:3], v168 offset:1024
	v_mfma_f32_16x16x32_bf16 v[124:127], v[4:7], v[242:245], v[124:127]
	s_waitcnt lgkmcnt(0)
	v_mfma_f32_16x16x32_bf16 v[12:15], v[0:3], v[242:245], v[174:177]
	v_mfma_f32_16x16x32_bf16 v[8:11], v[0:3], v[246:249], v[178:181]
	v_mfma_f32_16x16x32_bf16 v[4:7], v[0:3], v[206:209], v[182:185]
	v_mfma_f32_16x16x32_bf16 v[0:3], v[0:3], v[186:189], v[238:241]
	s_waitcnt vmcnt(0)
	s_add_u32 s66, s66, 0x100
	s_addc_u32 s67, s67, 0
	s_andn2_b64 vcc, exec, s[68:69]
	s_barrier
	s_cbranch_vccz .LBB0_205
.LBB0_203:
	v_mov_b32_e32 v134, v128
	ds_read_b128 v[170:173], v154
	ds_read_b128 v[174:177], v153 offset:32768
	ds_read_b128 v[178:181], v153 offset:34816
	ds_read_b128 v[182:185], v155
	ds_read_b128 v[186:189], v153 offset:36864
	ds_read_b128 v[190:193], v153 offset:38912
	v_lshlrev_b32_e32 v169, 4, v134
	s_waitcnt lgkmcnt(1)
	v_mfma_f32_16x16x32_bf16 v[194:197], v[170:173], v[186:189], v[116:119]
	v_and_b32_e32 v202, 32, v134
	s_nop 1
	v_lshlrev_b32_e32 v116, 9, v134
	v_and_b32_e32 v206, 0x7800, v116
	v_bfe_i32 v116, v134, 6, 22
	v_bfe_u32 v117, v134, 27, 1
	v_add_u32_e32 v117, v116, v117
	v_lshrrev_b32_e32 v117, 1, v117
	v_and_b32_e32 v203, 48, v169
	v_mul_i32_i24_e32 v117, 0x7f80, v117
	v_bitop3_b32 v117, v203, v117, v202 bitop3:0xde
	v_lshlrev_b32_e32 v116, 6, v116
	v_add3_u32 v134, v117, v206, v116
	ds_read_b128 v[116:119], v156
	v_lshl_add_u64 v[198:199], s[66:67], 0, v[134:135]
	v_mfma_f32_16x16x32_bf16 v[124:127], v[170:173], v[174:177], v[124:127]
	v_readfirstlane_b32 s24, v145
	s_mov_b32 m0, s24
	v_readfirstlane_b32 s24, v146
	v_mfma_f32_16x16x32_bf16 v[120:123], v[170:173], v[178:181], v[120:123]
	v_add_u32_e32 v134, 0x2000, v169
	v_ashrrev_i32_e32 v134, 10, v134
	s_waitcnt lgkmcnt(1)
	v_mfma_f32_16x16x32_bf16 v[112:115], v[170:173], v[190:193], v[112:115]
	v_lshl_add_u64 v[170:171], s[8:9], 0, v[198:199]
	v_lshl_add_u64 v[170:171], v[170:171], 0, s[80:81]
	global_load_lds_dwordx4 v[170:171], off
	v_mfma_f32_16x16x32_bf16 v[108:111], v[182:185], v[174:177], v[108:111]
	s_mov_b32 m0, s24
	ds_read_b128 v[170:173], v157
	v_readfirstlane_b32 s24, v147
	v_mfma_f32_16x16x32_bf16 v[104:107], v[182:185], v[178:181], v[104:107]
	v_mfma_f32_16x16x32_bf16 v[100:103], v[182:185], v[186:189], v[100:103]
	v_mfma_f32_16x16x32_bf16 v[96:99], v[182:185], v[190:193], v[96:99]
	v_lshl_add_u64 v[182:183], s[10:11], 0, v[198:199]
	v_lshl_add_u64 v[182:183], v[182:183], 0, s[80:81]
	global_load_lds_dwordx4 v[182:183], off
	v_lshrrev_b32_e32 v182, 31, v134
	v_add_u32_e32 v182, v134, v182
	s_waitcnt lgkmcnt(0)
	v_mfma_f32_16x16x32_bf16 v[92:95], v[116:119], v[174:177], v[92:95]
	s_mov_b32 m0, s24
	v_readfirstlane_b32 s24, v148
	v_mfma_f32_16x16x32_bf16 v[88:91], v[116:119], v[178:181], v[88:91]
	v_mfma_f32_16x16x32_bf16 v[84:87], v[116:119], v[186:189], v[84:87]
	v_mfma_f32_16x16x32_bf16 v[80:83], v[116:119], v[190:193], v[80:83]
	v_lshrrev_b32_e32 v116, 1, v182
	v_mul_lo_u32 v116, v116, s71
	v_bitop3_b32 v116, v203, v116, v202 bitop3:0xde
	v_lshlrev_b32_e32 v117, 6, v134
	v_add3_u32 v134, v116, v206, v117
	v_lshl_add_u64 v[182:183], s[66:67], 0, v[134:135]
	v_lshl_add_u64 v[116:117], s[8:9], 0, v[182:183]
	v_lshl_add_u64 v[184:185], v[116:117], 0, s[80:81]
	ds_read_b128 v[116:119], v158
	v_mfma_f32_16x16x32_bf16 v[76:79], v[170:173], v[174:177], v[76:79]
	v_lshl_add_u64 v[182:183], s[10:11], 0, v[182:183]
	global_load_lds_dwordx4 v[184:185], off
	v_mfma_f32_16x16x32_bf16 v[72:75], v[170:173], v[178:181], v[72:75]
	v_lshl_add_u64 v[182:183], v[182:183], 0, s[80:81]
	s_mov_b32 m0, s24
	v_add_u32_e32 v134, 0x4000, v169
	v_mfma_f32_16x16x32_bf16 v[68:71], v[170:173], v[186:189], v[68:71]
	global_load_lds_dwordx4 v[182:183], off
	v_readfirstlane_b32 s24, v149
	v_mfma_f32_16x16x32_bf16 v[64:67], v[170:173], v[190:193], v[64:67]
	ds_read_b128 v[170:173], v159
	s_mov_b32 m0, s24
	v_readfirstlane_b32 s24, v150
	s_waitcnt lgkmcnt(0)
	v_mfma_f32_16x16x32_bf16 v[182:185], v[116:119], v[178:181], v[56:59]
	s_nop 2
	v_ashrrev_i32_e32 v56, 10, v134
	v_lshrrev_b32_e32 v57, 31, v56
	v_add_u32_e32 v57, v56, v57
	v_mfma_f32_16x16x32_bf16 v[198:201], v[116:119], v[186:189], v[52:55]
	s_nop 2
	v_lshrrev_b32_e32 v52, 1, v57
	v_mfma_f32_16x16x32_bf16 v[222:225], v[170:173], v[186:189], v[36:39]
	v_mul_lo_u32 v52, v52, s71
	v_bitop3_b32 v52, v203, v52, v202 bitop3:0xde
	s_nop 0
	ds_read_b128 v[36:39], v160
	v_mfma_f32_16x16x32_bf16 v[210:213], v[116:119], v[190:193], v[48:51]
	s_nop 2
	v_lshlrev_b32_e32 v48, 6, v56
	v_add3_u32 v134, v52, v206, v48
	v_lshl_add_u64 v[48:49], s[66:67], 0, v[134:135]
	v_mfma_f32_16x16x32_bf16 v[214:217], v[170:173], v[174:177], v[44:47]
	s_nop 2
	v_lshl_add_u64 v[44:45], s[8:9], 0, v[48:49]
	v_lshl_add_u64 v[44:45], v[44:45], 0, s[80:81]
	v_mfma_f32_16x16x32_bf16 v[218:221], v[170:173], v[178:181], v[40:43]
	global_load_lds_dwordx4 v[44:45], off
	s_mov_b32 m0, s24
	s_nop 0
	v_lshl_add_u64 v[40:41], s[10:11], 0, v[48:49]
	v_lshl_add_u64 v[40:41], v[40:41], 0, s[80:81]
	global_load_lds_dwordx4 v[40:41], off
	v_add_u32_e32 v40, 0x6000, v169
	v_mfma_f32_16x16x32_bf16 v[170:173], v[170:173], v[190:193], v[32:35]
	v_readfirstlane_b32 s24, v151
	s_mov_b32 m0, s24
	v_readfirstlane_b32 s24, v152
	ds_read_b128 v[32:35], v161
	s_waitcnt lgkmcnt(0)
	v_mfma_f32_16x16x32_bf16 v[226:229], v[36:39], v[174:177], v[28:31]
	s_nop 2
	v_ashrrev_i32_e32 v28, 10, v40
	v_lshrrev_b32_e32 v29, 31, v28
	v_add_u32_e32 v29, v28, v29
	v_mfma_f32_16x16x32_bf16 v[230:233], v[36:39], v[178:181], v[24:27]
	s_nop 2
	v_lshrrev_b32_e32 v24, 1, v29
	v_mul_lo_u32 v24, v24, s71
	v_bitop3_b32 v24, v203, v24, v202 bitop3:0xde
	v_mfma_f32_16x16x32_bf16 v[234:237], v[36:39], v[186:189], v[20:23]
	s_nop 2
	v_lshlrev_b32_e32 v20, 6, v28
	v_add3_u32 v134, v24, v206, v20
	v_lshl_add_u64 v[20:21], s[66:67], 0, v[134:135]
	v_mfma_f32_16x16x32_bf16 v[238:241], v[36:39], v[190:193], v[16:19]
	s_nop 2
	v_lshl_add_u64 v[16:17], s[8:9], 0, v[20:21]
	v_lshl_add_u64 v[16:17], v[16:17], 0, s[80:81]
	v_mfma_f32_16x16x32_bf16 v[178:181], v[32:35], v[178:181], v[8:11]
	global_load_lds_dwordx4 v[16:17], off
	s_mov_b32 m0, s24
	s_nop 0
	v_lshl_add_u64 v[8:9], s[10:11], 0, v[20:21]
	v_lshl_add_u64 v[8:9], v[8:9], 0, s[80:81]
	global_load_lds_dwordx4 v[8:9], off
	v_mfma_f32_16x16x32_bf16 v[60:63], v[116:119], v[174:177], v[60:63]
	v_mfma_f32_16x16x32_bf16 v[4:7], v[32:35], v[186:189], v[4:7]
	v_mfma_f32_16x16x32_bf16 v[174:177], v[32:35], v[174:177], v[12:15]
	v_mfma_f32_16x16x32_bf16 v[186:189], v[32:35], v[190:193], v[0:3]
	s_nop 2
	ds_read_b128 v[0:3], v154 offset:1024
	ds_read_b128 v[190:193], v153 offset:33792
	ds_read_b128 v[36:39], v156 offset:1024
	ds_read_b128 v[52:55], v157 offset:1024
	ds_read_b128 v[242:245], v153 offset:35840
	ds_read_b128 v[246:249], v153 offset:37888
	s_waitcnt lgkmcnt(0)
	v_mfma_f32_16x16x32_bf16 v[116:119], v[0:3], v[242:245], v[120:123]
	ds_read_b128 v[20:23], v155 offset:1024
	v_mfma_f32_16x16x32_bf16 v[120:123], v[0:3], v[246:249], v[194:197]
	s_nop 2
	ds_read_b128 v[194:197], v153 offset:39936
	v_mfma_f32_16x16x32_bf16 v[32:35], v[36:39], v[246:249], v[84:87]
	v_mfma_f32_16x16x32_bf16 v[48:51], v[52:55], v[246:249], v[68:71]
	s_nop 1
	ds_read_b128 v[84:87], v159 offset:1024
	ds_read_b128 v[68:71], v158 offset:1024
	s_waitcnt lgkmcnt(3)
	v_mfma_f32_16x16x32_bf16 v[16:19], v[20:23], v[246:249], v[100:103]
	v_mfma_f32_16x16x32_bf16 v[24:27], v[36:39], v[190:193], v[92:95]
	s_nop 1
	ds_read_b128 v[100:103], v160 offset:1024
	v_mfma_f32_16x16x32_bf16 v[28:31], v[36:39], v[242:245], v[88:91]
	s_waitcnt lgkmcnt(3)
	v_mfma_f32_16x16x32_bf16 v[36:39], v[36:39], v[194:197], v[80:83]
	v_mfma_f32_16x16x32_bf16 v[40:43], v[52:55], v[190:193], v[76:79]
	v_mfma_f32_16x16x32_bf16 v[44:47], v[52:55], v[242:245], v[72:75]
	s_waitcnt lgkmcnt(2)
	v_mfma_f32_16x16x32_bf16 v[72:75], v[84:87], v[190:193], v[214:217]
	v_mfma_f32_16x16x32_bf16 v[76:79], v[84:87], v[242:245], v[218:221]
	v_mfma_f32_16x16x32_bf16 v[80:83], v[84:87], v[246:249], v[222:225]
	v_mfma_f32_16x16x32_bf16 v[84:87], v[84:87], v[194:197], v[170:173]
	s_nop 2
	ds_read_b128 v[170:173], v161 offset:1024
	v_mfma_f32_16x16x32_bf16 v[124:127], v[0:3], v[190:193], v[124:127]
	v_mfma_f32_16x16x32_bf16 v[0:3], v[0:3], v[194:197], v[112:115]
	v_mfma_f32_16x16x32_bf16 v[8:11], v[20:23], v[190:193], v[108:111]
	v_mfma_f32_16x16x32_bf16 v[12:15], v[20:23], v[242:245], v[104:107]
	v_mfma_f32_16x16x32_bf16 v[20:23], v[20:23], v[194:197], v[96:99]
	v_mfma_f32_16x16x32_bf16 v[52:55], v[52:55], v[194:197], v[64:67]
	s_waitcnt lgkmcnt(2)
	v_mfma_f32_16x16x32_bf16 v[56:59], v[68:71], v[190:193], v[60:63]
	v_mfma_f32_16x16x32_bf16 v[60:63], v[68:71], v[242:245], v[182:185]
	v_mfma_f32_16x16x32_bf16 v[64:67], v[68:71], v[246:249], v[198:201]
	v_mfma_f32_16x16x32_bf16 v[68:71], v[68:71], v[194:197], v[210:213]
	s_waitcnt lgkmcnt(1)
	v_mfma_f32_16x16x32_bf16 v[88:91], v[100:103], v[190:193], v[226:229]
	v_mfma_f32_16x16x32_bf16 v[92:95], v[100:103], v[242:245], v[230:233]
	v_mfma_f32_16x16x32_bf16 v[96:99], v[100:103], v[246:249], v[234:237]
	v_mfma_f32_16x16x32_bf16 v[100:103], v[100:103], v[194:197], v[238:241]
	s_waitcnt lgkmcnt(0)
	v_mfma_f32_16x16x32_bf16 v[104:107], v[170:173], v[190:193], v[174:177]
	v_mfma_f32_16x16x32_bf16 v[108:111], v[170:173], v[242:245], v[178:181]
	v_mfma_f32_16x16x32_bf16 v[112:115], v[170:173], v[246:249], v[4:7]
	v_mfma_f32_16x16x32_bf16 v[4:7], v[170:173], v[194:197], v[186:189]
	s_waitcnt vmcnt(0)
	s_cmp_gt_u32 s23, 13
	s_cselect_b64 s[68:69], -1, 0
	s_and_b64 vcc, exec, s[68:69]
	s_barrier
	s_cbranch_vccnz .LBB0_202
	v_mov_b32_e32 v134, v128
	v_readfirstlane_b32 s24, v129
	v_lshlrev_b32_e32 v170, 9, v134
	v_lshlrev_b32_e32 v169, 4, v134
	v_and_b32_e32 v174, 32, v134
	v_and_b32_e32 v176, 0x7800, v170
	v_bfe_i32 v170, v134, 6, 22
	v_bfe_u32 v134, v134, 27, 1
	v_add_u32_e32 v134, v170, v134
	v_lshrrev_b32_e32 v134, 1, v134
	v_and_b32_e32 v175, 48, v169
	v_mul_i32_i24_e32 v134, 0x7f80, v134
	v_bitop3_b32 v134, v175, v134, v174 bitop3:0xde
	v_lshlrev_b32_e32 v170, 6, v170
	v_add3_u32 v134, v134, v176, v170
	v_lshl_add_u64 v[170:171], s[66:67], 0, v[134:135]
	v_lshl_add_u64 v[172:173], s[8:9], 0, v[170:171]
	v_lshl_add_u64 v[172:173], v[172:173], 0, s[82:83]
	s_mov_b32 m0, s24
	v_lshl_add_u64 v[170:171], s[10:11], 0, v[170:171]
	v_readfirstlane_b32 s24, v130
	v_add_u32_e32 v134, 0x2000, v169
	global_load_lds_dwordx4 v[172:173], off
	v_lshl_add_u64 v[170:171], v[170:171], 0, s[82:83]
	s_mov_b32 m0, s24
	v_ashrrev_i32_e32 v134, 10, v134
	global_load_lds_dwordx4 v[170:171], off
	v_lshrrev_b32_e32 v170, 31, v134
	v_add_u32_e32 v170, v134, v170
	v_lshrrev_b32_e32 v170, 1, v170
	v_mul_lo_u32 v170, v170, s71
	v_bitop3_b32 v170, v175, v170, v174 bitop3:0xde
	v_lshlrev_b32_e32 v134, 6, v134
	v_add3_u32 v134, v170, v176, v134
	v_lshl_add_u64 v[170:171], s[66:67], 0, v[134:135]
	v_lshl_add_u64 v[172:173], s[8:9], 0, v[170:171]
	v_readfirstlane_b32 s24, v131
	v_lshl_add_u64 v[172:173], v[172:173], 0, s[82:83]
	s_mov_b32 m0, s24
	v_lshl_add_u64 v[170:171], s[10:11], 0, v[170:171]
	v_readfirstlane_b32 s24, v136
	v_add_u32_e32 v134, 0x4000, v169
	global_load_lds_dwordx4 v[172:173], off
	v_lshl_add_u64 v[170:171], v[170:171], 0, s[82:83]
	s_mov_b32 m0, s24
	v_ashrrev_i32_e32 v134, 10, v134
	global_load_lds_dwordx4 v[170:171], off
	v_lshrrev_b32_e32 v170, 31, v134
	v_add_u32_e32 v170, v134, v170
	v_lshrrev_b32_e32 v170, 1, v170
	v_mul_lo_u32 v170, v170, s71
	v_bitop3_b32 v170, v175, v170, v174 bitop3:0xde
	v_lshlrev_b32_e32 v134, 6, v134
	v_add3_u32 v134, v170, v176, v134
	v_lshl_add_u64 v[170:171], s[66:67], 0, v[134:135]
	v_add_u32_e32 v134, 0x6000, v169
	v_ashrrev_i32_e32 v134, 10, v134
	v_lshrrev_b32_e32 v169, 31, v134
	v_add_u32_e32 v169, v134, v169
	v_lshrrev_b32_e32 v169, 1, v169
	v_lshl_add_u64 v[172:173], s[8:9], 0, v[170:171]
	v_readfirstlane_b32 s24, v137
	v_mul_lo_u32 v169, v169, s71
	v_lshl_add_u64 v[172:173], v[172:173], 0, s[82:83]
	s_mov_b32 m0, s24
	v_lshl_add_u64 v[170:171], s[10:11], 0, v[170:171]
	v_readfirstlane_b32 s24, v138
	v_bitop3_b32 v169, v175, v169, v174 bitop3:0xde
	v_lshlrev_b32_e32 v134, 6, v134
	global_load_lds_dwordx4 v[172:173], off
	v_lshl_add_u64 v[170:171], v[170:171], 0, s[82:83]
	s_mov_b32 m0, s24
	v_add3_u32 v134, v169, v176, v134
	global_load_lds_dwordx4 v[170:171], off
	v_lshl_add_u64 v[170:171], s[66:67], 0, v[134:135]
	v_lshl_add_u64 v[172:173], s[8:9], 0, v[170:171]
	v_readfirstlane_b32 s24, v139
	v_lshl_add_u64 v[172:173], v[172:173], 0, s[82:83]
	s_mov_b32 m0, s24
	v_lshl_add_u64 v[170:171], s[10:11], 0, v[170:171]
	v_readfirstlane_b32 s24, v140
	global_load_lds_dwordx4 v[172:173], off
	v_lshl_add_u64 v[170:171], v[170:171], 0, s[82:83]
	s_mov_b32 m0, s24
	s_nop 0
	global_load_lds_dwordx4 v[170:171], off
	s_branch .LBB0_202

.LBB0_910:
	v_lshlrev_b32_e64 v39, v38, 1
	v_or_b32_e32 v39, v39, v30
	s_waitcnt lgkmcnt(11)
	v_cmp_ge_u32_e32 vcc, v26, v39
	s_bcnt1_i32_b64 s0, vcc
	v_cmp_ge_u32_e32 vcc, v27, v39
	s_bcnt1_i32_b64 s1, vcc
	s_waitcnt lgkmcnt(10)
	v_cmp_ge_u32_e32 vcc, v24, v39
	s_add_i32 s0, s1, s0
	s_bcnt1_i32_b64 s1, vcc
	v_cmp_ge_u32_e32 vcc, v25, v39
	s_add_i32 s0, s0, s1
	s_bcnt1_i32_b64 s1, vcc
	s_waitcnt lgkmcnt(9)
	v_cmp_ge_u32_e32 vcc, v22, v39
	s_add_i32 s0, s0, s1
	s_bcnt1_i32_b64 s1, vcc
	v_cmp_ge_u32_e32 vcc, v23, v39
	s_add_i32 s0, s0, s1
	s_bcnt1_i32_b64 s1, vcc
	s_waitcnt lgkmcnt(8)
	v_cmp_ge_u32_e32 vcc, v20, v39
	s_add_i32 s0, s0, s1
	s_bcnt1_i32_b64 s1, vcc
	v_cmp_ge_u32_e32 vcc, v21, v39
	s_add_i32 s0, s0, s1
	s_bcnt1_i32_b64 s1, vcc
	s_waitcnt lgkmcnt(7)
	v_cmp_ge_u32_e32 vcc, v18, v39
	s_add_i32 s0, s0, s1
	s_bcnt1_i32_b64 s1, vcc
	v_cmp_ge_u32_e32 vcc, v19, v39
	s_add_i32 s0, s0, s1
	s_bcnt1_i32_b64 s1, vcc
	s_waitcnt lgkmcnt(6)
	v_cmp_ge_u32_e32 vcc, v14, v39
	s_add_i32 s0, s0, s1
	s_bcnt1_i32_b64 s1, vcc
	v_cmp_ge_u32_e32 vcc, v15, v39
	s_add_i32 s0, s0, s1
	s_bcnt1_i32_b64 s1, vcc
	s_waitcnt lgkmcnt(5)
	v_cmp_ge_u32_e32 vcc, v12, v39
	s_add_i32 s0, s0, s1
	s_bcnt1_i32_b64 s1, vcc
	v_cmp_ge_u32_e32 vcc, v13, v39
	s_add_i32 s0, s0, s1
	s_bcnt1_i32_b64 s1, vcc
	s_waitcnt lgkmcnt(4)
	v_cmp_ge_u32_e32 vcc, v10, v39
	s_add_i32 s0, s0, s1
	s_bcnt1_i32_b64 s1, vcc
	v_cmp_ge_u32_e32 vcc, v11, v39
	s_add_i32 s0, s0, s1
	s_bcnt1_i32_b64 s1, vcc
	s_waitcnt lgkmcnt(3)
	v_cmp_ge_u32_e32 vcc, v8, v39
	s_add_i32 s0, s0, s1
	s_bcnt1_i32_b64 s1, vcc
	v_cmp_ge_u32_e32 vcc, v9, v39
	s_add_i32 s0, s0, s1
	s_bcnt1_i32_b64 s1, vcc
	s_waitcnt lgkmcnt(2)
	v_cmp_ge_u32_e32 vcc, v6, v39
	s_add_i32 s0, s0, s1
	s_bcnt1_i32_b64 s1, vcc
	v_cmp_ge_u32_e32 vcc, v7, v39
	s_add_i32 s0, s0, s1
	s_bcnt1_i32_b64 s1, vcc
	s_waitcnt lgkmcnt(1)
	v_cmp_ge_u32_e32 vcc, v4, v39
	s_add_i32 s0, s0, s1
	s_bcnt1_i32_b64 s1, vcc
	v_cmp_ge_u32_e32 vcc, v5, v39
	s_add_i32 s0, s0, s1
	s_bcnt1_i32_b64 s1, vcc
	s_waitcnt lgkmcnt(0)
	v_cmp_ge_u32_e32 vcc, v2, v39
	s_add_i32 s0, s0, s1
	s_bcnt1_i32_b64 s1, vcc
	v_cmp_ge_u32_e32 vcc, v3, v39
	s_add_i32 s0, s0, s1
	s_bcnt1_i32_b64 s1, vcc
	v_cmp_ge_u32_e32 vcc, v37, v39
	s_add_i32 s0, s0, s1
	s_bcnt1_i32_b64 s1, vcc
	v_cmp_ge_u32_e32 vcc, v36, v39
	s_add_i32 s0, s0, s1
	s_bcnt1_i32_b64 s1, vcc
	v_cmp_ge_u32_e32 vcc, v35, v39
	s_add_i32 s0, s0, s1
	s_bcnt1_i32_b64 s1, vcc
	v_cmp_ge_u32_e32 vcc, v34, v39
	s_add_i32 s0, s0, s1
	s_bcnt1_i32_b64 s1, vcc
	v_cmp_ge_u32_e32 vcc, v33, v39
	s_add_i32 s0, s0, s1
	s_bcnt1_i32_b64 s1, vcc
	v_cmp_ge_u32_e32 vcc, v32, v39
	s_add_i32 s0, s0, s1
	s_bcnt1_i32_b64 s1, vcc
	v_cmp_ge_u32_e32 vcc, v31, v39
	s_add_i32 s0, s0, s1
	s_bcnt1_i32_b64 s1, vcc
	v_cmp_ge_u32_e32 vcc, v29, v39
	s_add_i32 s0, s0, s1
	s_bcnt1_i32_b64 s1, vcc
	s_add_i32 s2, s0, s1
	s_cmpk_eq_i32 s2, 0x100
	s_cselect_b64 s[0:1], -1, 0
	s_cmpk_lt_u32 s2, 0x100
	s_cselect_b64 vcc, -1, 0
	v_cndmask_b32_e32 v30, v39, v30, vcc
	v_subrev_co_u32_e32 v38, vcc, 1, v38
	s_or_b64 s[0:1], s[0:1], vcc
	s_andn2_b64 vcc, exec, s[0:1]
	s_cbranch_vccnz .LBB0_910
	s_cmpk_eq_i32 s2, 0x100
	s_cbranch_scc1 .Lselfast_32
	v_cmp_gt_u32_e32 vcc, v26, v30
	s_bcnt1_i32_b64 s8, vcc
	v_cmp_gt_u32_e32 vcc, v27, v30
	s_bcnt1_i32_b64 s9, vcc
	v_cmp_gt_u32_e32 vcc, v24, v30
	s_bcnt1_i32_b64 s10, vcc
	v_cmp_gt_u32_e32 vcc, v25, v30
	s_add_i32 s8, s8, s9
	s_bcnt1_i32_b64 s11, vcc
	v_cmp_gt_u32_e32 vcc, v22, v30
	s_add_i32 s8, s8, s10
	s_bcnt1_i32_b64 s64, vcc
	v_cmp_gt_u32_e32 vcc, v23, v30
	s_add_i32 s8, s8, s11
	s_bcnt1_i32_b64 s65, vcc
	v_cmp_gt_u32_e32 vcc, v20, v30
	s_add_i32 s8, s8, s64
	s_bcnt1_i32_b64 s66, vcc
	v_cmp_gt_u32_e32 vcc, v21, v30
	s_add_i32 s8, s8, s65
	s_bcnt1_i32_b64 s67, vcc
	v_cmp_gt_u32_e32 vcc, v18, v30
	s_add_i32 s64, s8, s66
	s_bcnt1_i32_b64 s68, vcc
	v_cmp_gt_u32_e32 vcc, v19, v30
	s_add_i32 s64, s64, s67
	s_bcnt1_i32_b64 s69, vcc
	v_cmp_gt_u32_e32 vcc, v14, v30
	s_add_i32 s64, s64, s68
	s_bcnt1_i32_b64 s73, vcc
	v_cmp_gt_u32_e32 vcc, v15, v30
	s_add_i32 s64, s64, s69
	s_bcnt1_i32_b64 s74, vcc
	v_cmp_gt_u32_e32 vcc, v12, v30
	s_add_i32 s64, s64, s73
	s_bcnt1_i32_b64 s75, vcc
	v_cmp_gt_u32_e32 vcc, v13, v30
	s_add_i32 s64, s64, s74
	s_bcnt1_i32_b64 s76, vcc
	v_cmp_gt_u32_e32 vcc, v10, v30
	s_add_i32 s64, s64, s75
	s_bcnt1_i32_b64 s77, vcc
	v_cmp_gt_u32_e32 vcc, v11, v30
	s_add_i32 s64, s64, s76
	s_bcnt1_i32_b64 s78, vcc
	v_cmp_gt_u32_e32 vcc, v8, v30
	s_add_i32 s64, s64, s77
	s_bcnt1_i32_b64 s79, vcc
	v_cmp_gt_u32_e32 vcc, v9, v30
	s_add_i32 s64, s64, s78
	s_bcnt1_i32_b64 s80, vcc
	v_cmp_gt_u32_e32 vcc, v6, v30
	s_add_i32 s64, s64, s79
	s_bcnt1_i32_b64 s81, vcc
	v_cmp_gt_u32_e32 vcc, v7, v30
	s_add_i32 s64, s64, s80
	s_bcnt1_i32_b64 s82, vcc
	v_cmp_gt_u32_e32 vcc, v4, v30
	s_add_i32 s64, s64, s81
	s_bcnt1_i32_b64 s83, vcc
	v_cmp_gt_u32_e32 vcc, v5, v30
	s_add_i32 s64, s64, s82
	s_bcnt1_i32_b64 s84, vcc
	v_cmp_gt_u32_e32 vcc, v2, v30
	s_add_i32 s64, s64, s83
	s_bcnt1_i32_b64 s85, vcc
	v_cmp_gt_u32_e32 vcc, v3, v30
	s_add_i32 s64, s64, s84
	s_bcnt1_i32_b64 s86, vcc
	v_cmp_gt_u32_e32 vcc, v37, v30
	s_add_i32 s64, s64, s85
	s_bcnt1_i32_b64 s87, vcc
	v_cmp_gt_u32_e32 vcc, v36, v30
	s_add_i32 s64, s64, s86
	s_bcnt1_i32_b64 s88, vcc
	v_cmp_gt_u32_e32 vcc, v35, v30
	s_add_i32 s64, s64, s87
	s_bcnt1_i32_b64 s89, vcc
	v_cmp_gt_u32_e32 vcc, v34, v30
	s_add_i32 s64, s64, s88
	s_bcnt1_i32_b64 s90, vcc
	v_cmp_gt_u32_e32 vcc, v33, v30
	s_add_i32 s64, s64, s89
	s_bcnt1_i32_b64 s91, vcc
	v_cmp_gt_u32_e32 vcc, v32, v30
	s_add_i32 s64, s64, s90
	s_bcnt1_i32_b64 s92, vcc
	v_cmp_gt_u32_e32 vcc, v31, v30
	s_add_i32 s64, s64, s91
	s_bcnt1_i32_b64 s93, vcc
	v_cmp_gt_u32_e32 vcc, v29, v30
	s_add_i32 s64, s64, s92
	s_bcnt1_i32_b64 s94, vcc
	s_add_i32 s64, s64, s93
	s_add_i32 s64, s64, s94
	v_cmp_le_u32_e64 s[62:63], v26, v30
	v_cmp_le_u32_e64 s[60:61], v27, v30
	v_cmp_le_u32_e64 s[58:59], v24, v30
	v_cmp_le_u32_e64 s[56:57], v25, v30
	v_cmp_le_u32_e64 s[54:55], v22, v30
	v_cmp_le_u32_e64 s[52:53], v23, v30
	v_cmp_le_u32_e64 s[50:51], v20, v30
	v_cmp_le_u32_e64 s[48:49], v21, v30
	v_cmp_le_u32_e64 s[46:47], v18, v30
	v_cmp_le_u32_e64 s[44:45], v19, v30
	v_cmp_le_u32_e64 s[42:43], v14, v30
	v_cmp_le_u32_e64 s[40:41], v15, v30
	v_cmp_le_u32_e64 s[38:39], v12, v30
	v_cmp_le_u32_e64 s[36:37], v13, v30
	v_cmp_le_u32_e64 s[34:35], v10, v30
	v_cmp_le_u32_e64 s[30:31], v11, v30
	v_cmp_le_u32_e64 s[28:29], v8, v30
	v_cmp_le_u32_e64 s[26:27], v9, v30
	v_cmp_le_u32_e64 s[24:25], v6, v30
	v_cmp_le_u32_e64 s[22:23], v7, v30
	v_cmp_le_u32_e64 s[4:5], v4, v30
	v_cmp_le_u32_e64 s[0:1], v5, v30
	v_cmp_le_u32_e64 s[2:3], v2, v30
	v_cmp_le_u32_e64 s[6:7], v3, v30
	v_cmp_le_u32_e64 s[20:21], v37, v30
	v_cmp_le_u32_e64 s[18:19], v36, v30
	v_cmp_le_u32_e64 s[16:17], v35, v30
	v_cmp_le_u32_e64 s[14:15], v34, v30
	v_cmp_le_u32_e64 s[12:13], v33, v30
	v_cmp_le_u32_e64 s[10:11], v32, v30
	v_cmp_le_u32_e64 s[8:9], v31, v30
	v_cmp_le_u32_e32 vcc, v29, v30
	s_sub_i32 s73, 0x100, s64
	v_cmp_eq_u32_e64 s[64:65], v26, v30
	s_mov_b64 s[68:69], -1
	s_and_saveexec_b64 s[66:67], s[62:63]
	v_mbcnt_lo_u32_b32 v26, s64, 0
	v_mbcnt_hi_u32_b32 v26, s65, v26
	v_cmp_gt_i32_e64 s[62:63], s73, v26
	s_and_b64 s[62:63], s[64:65], s[62:63]
	s_orn2_b64 s[68:69], s[62:63], exec
	s_or_b64 exec, exec, s[66:67]
	v_cndmask_b32_e64 v26, 0, 1, s[68:69]
	v_cmp_eq_u32_e64 s[66:67], 0, v16
	v_cmp_ne_u32_e64 s[68:69], 0, v26
	s_and_saveexec_b64 s[62:63], s[66:67]
	s_cbranch_execz .LBB0_915
	v_mov_b64_e32 v[38:39], s[68:69]
	global_store_dwordx2 v[0:1], v[38:39], off

.Lselfast_32:
	v_cmp_ge_u32_e64 s[4:5], v26, v30
	v_cmp_ge_u32_e64 s[6:7], v27, v30
	v_cmp_ge_u32_e64 s[8:9], v24, v30
	v_cmp_ge_u32_e64 s[10:11], v25, v30
	v_cmp_ge_u32_e64 s[12:13], v22, v30
	v_cmp_ge_u32_e64 s[14:15], v23, v30
	v_cmp_ge_u32_e64 s[16:17], v20, v30
	v_cmp_ge_u32_e64 s[18:19], v21, v30
	v_writelane_b32 v108, s4, 0
	v_writelane_b32 v109, s5, 0
	v_writelane_b32 v108, s6, 1
	v_writelane_b32 v109, s7, 1
	v_writelane_b32 v108, s8, 2
	v_writelane_b32 v109, s9, 2
	v_writelane_b32 v108, s10, 3
	v_writelane_b32 v109, s11, 3
	v_writelane_b32 v108, s12, 4
	v_writelane_b32 v109, s13, 4
	v_writelane_b32 v108, s14, 5
	v_writelane_b32 v109, s15, 5
	v_writelane_b32 v108, s16, 6
	v_writelane_b32 v109, s17, 6
	v_writelane_b32 v108, s18, 7
	v_writelane_b32 v109, s19, 7
	v_cmp_ge_u32_e64 s[4:5], v18, v30
	v_cmp_ge_u32_e64 s[6:7], v19, v30
	v_cmp_ge_u32_e64 s[8:9], v14, v30
	v_cmp_ge_u32_e64 s[10:11], v15, v30
	v_cmp_ge_u32_e64 s[12:13], v12, v30
	v_cmp_ge_u32_e64 s[14:15], v13, v30
	v_cmp_ge_u32_e64 s[16:17], v10, v30
	v_cmp_ge_u32_e64 s[18:19], v11, v30
	v_writelane_b32 v108, s4, 8
	v_writelane_b32 v109, s5, 8
	v_writelane_b32 v108, s6, 9
	v_writelane_b32 v109, s7, 9
	v_writelane_b32 v108, s8, 10
	v_writelane_b32 v109, s9, 10
	v_writelane_b32 v108, s10, 11
	v_writelane_b32 v109, s11, 11
	v_writelane_b32 v108, s12, 12
	v_writelane_b32 v109, s13, 12
	v_writelane_b32 v108, s14, 13
	v_writelane_b32 v109, s15, 13
	v_writelane_b32 v108, s16, 14
	v_writelane_b32 v109, s17, 14
	v_writelane_b32 v108, s18, 15
	v_writelane_b32 v109, s19, 15
	v_cmp_ge_u32_e64 s[4:5], v8, v30
	v_cmp_ge_u32_e64 s[6:7], v9, v30
	v_cmp_ge_u32_e64 s[8:9], v6, v30
	v_cmp_ge_u32_e64 s[10:11], v7, v30
	v_cmp_ge_u32_e64 s[12:13], v4, v30
	v_cmp_ge_u32_e64 s[14:15], v5, v30
	v_cmp_ge_u32_e64 s[16:17], v2, v30
	v_cmp_ge_u32_e64 s[18:19], v3, v30
	v_writelane_b32 v108, s4, 16
	v_writelane_b32 v109, s5, 16
	v_writelane_b32 v108, s6, 17
	v_writelane_b32 v109, s7, 17
	v_writelane_b32 v108, s8, 18
	v_writelane_b32 v109, s9, 18
	v_writelane_b32 v108, s10, 19
	v_writelane_b32 v109, s11, 19
	v_writelane_b32 v108, s12, 20
	v_writelane_b32 v109, s13, 20
	v_writelane_b32 v108, s14, 21
	v_writelane_b32 v109, s15, 21
	v_writelane_b32 v108, s16, 22
	v_writelane_b32 v109, s17, 22
	v_writelane_b32 v108, s18, 23
	v_writelane_b32 v109, s19, 23
	v_cmp_ge_u32_e64 s[4:5], v37, v30
	v_cmp_ge_u32_e64 s[6:7], v36, v30
	v_cmp_ge_u32_e64 s[8:9], v35, v30
	v_cmp_ge_u32_e64 s[10:11], v34, v30
	v_cmp_ge_u32_e64 s[12:13], v33, v30
	v_cmp_ge_u32_e64 s[14:15], v32, v30
	v_cmp_ge_u32_e64 s[16:17], v31, v30
	v_cmp_ge_u32_e64 s[18:19], v29, v30
	v_writelane_b32 v108, s4, 24
	v_writelane_b32 v109, s5, 24
	v_writelane_b32 v108, s6, 25
	v_writelane_b32 v109, s7, 25
	v_writelane_b32 v108, s8, 26
	v_writelane_b32 v109, s9, 26
	v_writelane_b32 v108, s10, 27
	v_writelane_b32 v109, s11, 27
	v_writelane_b32 v108, s12, 28
	v_writelane_b32 v109, s13, 28
	v_writelane_b32 v108, s14, 29
	v_writelane_b32 v109, s15, 29
	v_writelane_b32 v108, s16, 30
	v_writelane_b32 v109, s17, 30
	v_writelane_b32 v108, s18, 31
	v_writelane_b32 v109, s19, 31
	v_lshlrev_b32_e32 v110, 3, v16
	v_cmp_gt_u32_e32 vcc, 32, v16
	v_add_co_u32_e64 v110, s[4:5], v0, v110
	s_nop 1
	v_addc_co_u32_e64 v111, s[4:5], 0, v1, s[4:5]
	s_and_saveexec_b64 s[4:5], vcc
	global_store_dwordx2 v[110:111], v[108:109], off
	s_or_b64 exec, exec, s[4:5]
	s_branch .LBB0_1292
.Lselfast_24:
	v_cmp_ge_u32_e64 s[4:5], v18, v21
	v_cmp_ge_u32_e64 s[6:7], v19, v21
	v_cmp_ge_u32_e64 s[8:9], v14, v21
	v_cmp_ge_u32_e64 s[10:11], v15, v21
	v_cmp_ge_u32_e64 s[12:13], v12, v21
	v_cmp_ge_u32_e64 s[14:15], v13, v21
	v_cmp_ge_u32_e64 s[16:17], v10, v21
	v_cmp_ge_u32_e64 s[18:19], v11, v21
	v_writelane_b32 v108, s4, 0
	v_writelane_b32 v109, s5, 0
	v_writelane_b32 v108, s6, 1
	v_writelane_b32 v109, s7, 1
	v_writelane_b32 v108, s8, 2
	v_writelane_b32 v109, s9, 2
	v_writelane_b32 v108, s10, 3
	v_writelane_b32 v109, s11, 3
	v_writelane_b32 v108, s12, 4
	v_writelane_b32 v109, s13, 4
	v_writelane_b32 v108, s14, 5
	v_writelane_b32 v109, s15, 5
	v_writelane_b32 v108, s16, 6
	v_writelane_b32 v109, s17, 6
	v_writelane_b32 v108, s18, 7
	v_writelane_b32 v109, s19, 7
	v_cmp_ge_u32_e64 s[4:5], v8, v21
	v_cmp_ge_u32_e64 s[6:7], v9, v21
	v_cmp_ge_u32_e64 s[8:9], v6, v21
	v_cmp_ge_u32_e64 s[10:11], v7, v21
	v_cmp_ge_u32_e64 s[12:13], v4, v21
	v_cmp_ge_u32_e64 s[14:15], v5, v21
	v_cmp_ge_u32_e64 s[16:17], v2, v21
	v_cmp_ge_u32_e64 s[18:19], v3, v21
	v_writelane_b32 v108, s4, 8
	v_writelane_b32 v109, s5, 8
	v_writelane_b32 v108, s6, 9
	v_writelane_b32 v109, s7, 9
	v_writelane_b32 v108, s8, 10
	v_writelane_b32 v109, s9, 10
	v_writelane_b32 v108, s10, 11
	v_writelane_b32 v109, s11, 11
	v_writelane_b32 v108, s12, 12
	v_writelane_b32 v109, s13, 12
	v_writelane_b32 v108, s14, 13
	v_writelane_b32 v109, s15, 13
	v_writelane_b32 v108, s16, 14
	v_writelane_b32 v109, s17, 14
	v_writelane_b32 v108, s18, 15
	v_writelane_b32 v109, s19, 15
	v_cmp_ge_u32_e64 s[4:5], v29, v21
	v_cmp_ge_u32_e64 s[6:7], v27, v21
	v_cmp_ge_u32_e64 s[8:9], v26, v21
	v_cmp_ge_u32_e64 s[10:11], v25, v21
	v_cmp_ge_u32_e64 s[12:13], v24, v21
	v_cmp_ge_u32_e64 s[14:15], v23, v21
	v_cmp_ge_u32_e64 s[16:17], v22, v21
	v_cmp_ge_u32_e64 s[18:19], v20, v21
	v_writelane_b32 v108, s4, 16
	v_writelane_b32 v109, s5, 16
	v_writelane_b32 v108, s6, 17
	v_writelane_b32 v109, s7, 17
	v_writelane_b32 v108, s8, 18
	v_writelane_b32 v109, s9, 18
	v_writelane_b32 v108, s10, 19
	v_writelane_b32 v109, s11, 19
	v_writelane_b32 v108, s12, 20
	v_writelane_b32 v109, s13, 20
	v_writelane_b32 v108, s14, 21
	v_writelane_b32 v109, s15, 21
	v_writelane_b32 v108, s16, 22
	v_writelane_b32 v109, s17, 22
	v_writelane_b32 v108, s18, 23
	v_writelane_b32 v109, s19, 23
	v_lshlrev_b32_e32 v110, 3, v16
	v_cmp_gt_u32_e32 vcc, 24, v16
	v_add_co_u32_e64 v110, s[4:5], v0, v110
	s_nop 1
	v_addc_co_u32_e64 v111, s[4:5], 0, v1, s[4:5]
	s_and_saveexec_b64 s[4:5], vcc
	global_store_dwordx2 v[110:111], v[108:109], off
	s_or_b64 exec, exec, s[4:5]
	s_branch .LBB0_1292
.Lselfast_16:
	v_cmp_ge_u32_e64 s[4:5], v8, v11
	v_cmp_ge_u32_e64 s[6:7], v9, v11
	v_cmp_ge_u32_e64 s[8:9], v6, v11
	v_cmp_ge_u32_e64 s[10:11], v7, v11
	v_cmp_ge_u32_e64 s[12:13], v4, v11
	v_cmp_ge_u32_e64 s[14:15], v5, v11
	v_cmp_ge_u32_e64 s[16:17], v2, v11
	v_cmp_ge_u32_e64 s[18:19], v3, v11
	v_writelane_b32 v108, s4, 0
	v_writelane_b32 v109, s5, 0
	v_writelane_b32 v108, s6, 1
	v_writelane_b32 v109, s7, 1
	v_writelane_b32 v108, s8, 2
	v_writelane_b32 v109, s9, 2
	v_writelane_b32 v108, s10, 3
	v_writelane_b32 v109, s11, 3
	v_writelane_b32 v108, s12, 4
	v_writelane_b32 v109, s13, 4
	v_writelane_b32 v108, s14, 5
	v_writelane_b32 v109, s15, 5
	v_writelane_b32 v108, s16, 6
	v_writelane_b32 v109, s17, 6
	v_writelane_b32 v108, s18, 7
	v_writelane_b32 v109, s19, 7
	v_cmp_ge_u32_e64 s[4:5], v20, v11
	v_cmp_ge_u32_e64 s[6:7], v19, v11
	v_cmp_ge_u32_e64 s[8:9], v18, v11
	v_cmp_ge_u32_e64 s[10:11], v15, v11
	v_cmp_ge_u32_e64 s[12:13], v14, v11
	v_cmp_ge_u32_e64 s[14:15], v13, v11
	v_cmp_ge_u32_e64 s[16:17], v12, v11
	v_cmp_ge_u32_e64 s[18:19], v10, v11
	v_writelane_b32 v108, s4, 8
	v_writelane_b32 v109, s5, 8
	v_writelane_b32 v108, s6, 9
	v_writelane_b32 v109, s7, 9
	v_writelane_b32 v108, s8, 10
	v_writelane_b32 v109, s9, 10
	v_writelane_b32 v108, s10, 11
	v_writelane_b32 v109, s11, 11
	v_writelane_b32 v108, s12, 12
	v_writelane_b32 v109, s13, 12
	v_writelane_b32 v108, s14, 13
	v_writelane_b32 v109, s15, 13
	v_writelane_b32 v108, s16, 14
	v_writelane_b32 v109, s17, 14
	v_writelane_b32 v108, s18, 15
	v_writelane_b32 v109, s19, 15
	v_lshlrev_b32_e32 v110, 3, v16
	v_cmp_gt_u32_e32 vcc, 16, v16
	v_add_co_u32_e64 v110, s[4:5], v0, v110
	s_nop 1
	v_addc_co_u32_e64 v111, s[4:5], 0, v1, s[4:5]
	s_and_saveexec_b64 s[4:5], vcc
	global_store_dwordx2 v[110:111], v[108:109], off
	s_or_b64 exec, exec, s[4:5]
	s_branch .LBB0_1292
.Lselfast_8:
	v_cmp_ge_u32_e64 s[4:5], v10, v4
	v_cmp_ge_u32_e64 s[6:7], v9, v4
	v_cmp_ge_u32_e64 s[8:9], v8, v4
	v_cmp_ge_u32_e64 s[10:11], v7, v4
	v_cmp_ge_u32_e64 s[12:13], v6, v4
	v_cmp_ge_u32_e64 s[14:15], v5, v4
	v_cmp_ge_u32_e64 s[16:17], v3, v4
	v_cmp_ge_u32_e64 s[18:19], v2, v4
	v_writelane_b32 v108, s4, 0
	v_writelane_b32 v109, s5, 0
	v_writelane_b32 v108, s6, 1
	v_writelane_b32 v109, s7, 1
	v_writelane_b32 v108, s8, 2
	v_writelane_b32 v109, s9, 2
	v_writelane_b32 v108, s10, 3
	v_writelane_b32 v109, s11, 3
	v_writelane_b32 v108, s12, 4
	v_writelane_b32 v109, s13, 4
	v_writelane_b32 v108, s14, 5
	v_writelane_b32 v109, s15, 5
	v_writelane_b32 v108, s16, 6
	v_writelane_b32 v109, s17, 6
	v_writelane_b32 v108, s18, 7
	v_writelane_b32 v109, s19, 7
	v_lshlrev_b32_e32 v110, 3, v16
	v_cmp_gt_u32_e32 vcc, 8, v16
	v_add_co_u32_e64 v110, s[4:5], v0, v110
	s_nop 1
	v_addc_co_u32_e64 v111, s[4:5], 0, v1, s[4:5]
	s_and_saveexec_b64 s[4:5], vcc
	global_store_dwordx2 v[110:111], v[108:109], off
	s_or_b64 exec, exec, s[4:5]
	s_branch .LBB0_1292

.LBB0_1062:
	v_lshlrev_b32_e64 v31, v30, 1
	v_or_b32_e32 v31, v31, v21
	s_waitcnt lgkmcnt(7)
	v_cmp_ge_u32_e32 vcc, v18, v31
	s_bcnt1_i32_b64 s0, vcc
	v_cmp_ge_u32_e32 vcc, v19, v31
	s_bcnt1_i32_b64 s1, vcc
	s_waitcnt lgkmcnt(6)
	v_cmp_ge_u32_e32 vcc, v14, v31
	s_add_i32 s0, s1, s0
	s_bcnt1_i32_b64 s1, vcc
	v_cmp_ge_u32_e32 vcc, v15, v31
	s_add_i32 s0, s0, s1
	s_bcnt1_i32_b64 s1, vcc
	s_waitcnt lgkmcnt(5)
	v_cmp_ge_u32_e32 vcc, v12, v31
	s_add_i32 s0, s0, s1
	s_bcnt1_i32_b64 s1, vcc
	v_cmp_ge_u32_e32 vcc, v13, v31
	s_add_i32 s0, s0, s1
	s_bcnt1_i32_b64 s1, vcc
	s_waitcnt lgkmcnt(4)
	v_cmp_ge_u32_e32 vcc, v10, v31
	s_add_i32 s0, s0, s1
	s_bcnt1_i32_b64 s1, vcc
	v_cmp_ge_u32_e32 vcc, v11, v31
	s_add_i32 s0, s0, s1
	s_bcnt1_i32_b64 s1, vcc
	s_waitcnt lgkmcnt(3)
	v_cmp_ge_u32_e32 vcc, v8, v31
	s_add_i32 s0, s0, s1
	s_bcnt1_i32_b64 s1, vcc
	v_cmp_ge_u32_e32 vcc, v9, v31
	s_add_i32 s0, s0, s1
	s_bcnt1_i32_b64 s1, vcc
	s_waitcnt lgkmcnt(2)
	v_cmp_ge_u32_e32 vcc, v6, v31
	s_add_i32 s0, s0, s1
	s_bcnt1_i32_b64 s1, vcc
	v_cmp_ge_u32_e32 vcc, v7, v31
	s_add_i32 s0, s0, s1
	s_bcnt1_i32_b64 s1, vcc
	s_waitcnt lgkmcnt(1)
	v_cmp_ge_u32_e32 vcc, v4, v31
	s_add_i32 s0, s0, s1
	s_bcnt1_i32_b64 s1, vcc
	v_cmp_ge_u32_e32 vcc, v5, v31
	s_add_i32 s0, s0, s1
	s_bcnt1_i32_b64 s1, vcc
	s_waitcnt lgkmcnt(0)
	v_cmp_ge_u32_e32 vcc, v2, v31
	s_add_i32 s0, s0, s1
	s_bcnt1_i32_b64 s1, vcc
	v_cmp_ge_u32_e32 vcc, v3, v31
	s_add_i32 s0, s0, s1
	s_bcnt1_i32_b64 s1, vcc
	v_cmp_ge_u32_e32 vcc, v29, v31
	s_add_i32 s0, s0, s1
	s_bcnt1_i32_b64 s1, vcc
	v_cmp_ge_u32_e32 vcc, v27, v31
	s_add_i32 s0, s0, s1
	s_bcnt1_i32_b64 s1, vcc
	v_cmp_ge_u32_e32 vcc, v26, v31
	s_add_i32 s0, s0, s1
	s_bcnt1_i32_b64 s1, vcc
	v_cmp_ge_u32_e32 vcc, v25, v31
	s_add_i32 s0, s0, s1
	s_bcnt1_i32_b64 s1, vcc
	v_cmp_ge_u32_e32 vcc, v24, v31
	s_add_i32 s0, s0, s1
	s_bcnt1_i32_b64 s1, vcc
	v_cmp_ge_u32_e32 vcc, v23, v31
	s_add_i32 s0, s0, s1
	s_bcnt1_i32_b64 s1, vcc
	v_cmp_ge_u32_e32 vcc, v22, v31
	s_add_i32 s0, s0, s1
	s_bcnt1_i32_b64 s1, vcc
	v_cmp_ge_u32_e32 vcc, v20, v31
	s_add_i32 s0, s0, s1
	s_bcnt1_i32_b64 s1, vcc
	s_add_i32 s2, s0, s1
	s_cmpk_eq_i32 s2, 0x100
	s_cselect_b64 s[0:1], -1, 0
	s_cmpk_lt_u32 s2, 0x100
	s_cselect_b64 vcc, -1, 0
	v_cndmask_b32_e32 v21, v31, v21, vcc
	v_subrev_co_u32_e32 v30, vcc, 1, v30
	s_or_b64 s[0:1], s[0:1], vcc
	s_andn2_b64 vcc, exec, s[0:1]
	s_cbranch_vccnz .LBB0_1062
	s_cmpk_eq_i32 s2, 0x100
	s_cbranch_scc1 .Lselfast_24
	v_cmp_gt_u32_e32 vcc, v18, v21
	s_bcnt1_i32_b64 s50, vcc
	v_cmp_gt_u32_e32 vcc, v19, v21
	s_bcnt1_i32_b64 s51, vcc
	v_cmp_gt_u32_e32 vcc, v14, v21
	v_cmp_gt_u32_e64 s[48:49], v20, v21
	s_bcnt1_i32_b64 s52, vcc
	v_cmp_gt_u32_e32 vcc, v15, v21
	s_bcnt1_i32_b64 s48, s[48:49]
	s_add_i32 s49, s50, s51
	s_bcnt1_i32_b64 s53, vcc
	v_cmp_gt_u32_e32 vcc, v12, v21
	s_add_i32 s49, s49, s52
	s_bcnt1_i32_b64 s54, vcc
	v_cmp_gt_u32_e32 vcc, v13, v21
	s_add_i32 s49, s49, s53
	s_bcnt1_i32_b64 s55, vcc
	v_cmp_gt_u32_e32 vcc, v10, v21
	s_add_i32 s49, s49, s54
	s_bcnt1_i32_b64 s56, vcc
	v_cmp_gt_u32_e32 vcc, v11, v21
	s_add_i32 s49, s49, s55
	s_bcnt1_i32_b64 s57, vcc
	v_cmp_gt_u32_e32 vcc, v8, v21
	s_add_i32 s49, s49, s56
	s_bcnt1_i32_b64 s58, vcc
	v_cmp_gt_u32_e32 vcc, v9, v21
	s_add_i32 s49, s49, s57
	s_bcnt1_i32_b64 s59, vcc
	v_cmp_gt_u32_e32 vcc, v6, v21
	s_add_i32 s49, s49, s58
	s_bcnt1_i32_b64 s60, vcc
	v_cmp_gt_u32_e32 vcc, v7, v21
	s_add_i32 s49, s49, s59
	s_bcnt1_i32_b64 s61, vcc
	v_cmp_gt_u32_e32 vcc, v4, v21
	s_add_i32 s49, s49, s60
	s_bcnt1_i32_b64 s62, vcc
	v_cmp_gt_u32_e32 vcc, v5, v21
	s_add_i32 s49, s49, s61
	s_bcnt1_i32_b64 s63, vcc
	v_cmp_gt_u32_e32 vcc, v2, v21
	s_add_i32 s49, s49, s62
	s_bcnt1_i32_b64 s64, vcc
	v_cmp_gt_u32_e32 vcc, v3, v21
	s_add_i32 s49, s49, s63
	s_bcnt1_i32_b64 s65, vcc
	v_cmp_gt_u32_e32 vcc, v29, v21
	s_add_i32 s49, s49, s64
	s_bcnt1_i32_b64 s66, vcc
	v_cmp_gt_u32_e32 vcc, v27, v21
	s_add_i32 s49, s49, s65
	s_bcnt1_i32_b64 s67, vcc
	v_cmp_gt_u32_e32 vcc, v26, v21
	s_add_i32 s49, s49, s66
	s_bcnt1_i32_b64 s68, vcc
	v_cmp_gt_u32_e32 vcc, v25, v21
	s_add_i32 s49, s49, s67
	s_bcnt1_i32_b64 s69, vcc
	v_cmp_gt_u32_e32 vcc, v24, v21
	s_add_i32 s49, s49, s68
	s_bcnt1_i32_b64 s73, vcc
	v_cmp_gt_u32_e32 vcc, v23, v21
	s_add_i32 s49, s49, s69
	s_bcnt1_i32_b64 s74, vcc
	v_cmp_gt_u32_e32 vcc, v22, v21
	s_add_i32 s49, s49, s73
	s_bcnt1_i32_b64 s75, vcc
	s_add_i32 s49, s49, s74
	s_add_i32 s49, s49, s75
	s_add_i32 s49, s49, s48
	v_cmp_le_u32_e64 s[46:47], v18, v21
	v_cmp_le_u32_e64 s[44:45], v19, v21
	v_cmp_le_u32_e64 s[42:43], v14, v21
	v_cmp_le_u32_e64 s[40:41], v15, v21
	v_cmp_le_u32_e64 s[38:39], v12, v21
	v_cmp_le_u32_e64 s[36:37], v13, v21
	v_cmp_le_u32_e64 s[34:35], v10, v21
	v_cmp_le_u32_e64 s[30:31], v11, v21
	v_cmp_le_u32_e64 s[28:29], v8, v21
	v_cmp_le_u32_e64 s[26:27], v9, v21
	v_cmp_le_u32_e64 s[24:25], v6, v21
	v_cmp_le_u32_e64 s[22:23], v7, v21
	v_cmp_le_u32_e64 s[20:21], v4, v21
	v_cmp_le_u32_e64 s[18:19], v5, v21
	v_cmp_le_u32_e64 s[16:17], v2, v21
	v_cmp_le_u32_e64 s[14:15], v3, v21
	v_cmp_le_u32_e64 s[12:13], v29, v21
	v_cmp_le_u32_e64 s[10:11], v27, v21
	v_cmp_le_u32_e64 s[8:9], v26, v21
	v_cmp_le_u32_e64 s[6:7], v25, v21
	v_cmp_le_u32_e64 s[4:5], v24, v21
	v_cmp_le_u32_e64 s[2:3], v23, v21
	v_cmp_le_u32_e64 s[0:1], v22, v21
	v_cmp_le_u32_e32 vcc, v20, v21
	s_sub_i32 s54, 0x100, s49
	v_cmp_eq_u32_e64 s[48:49], v18, v21
	s_mov_b64 s[52:53], -1
	s_and_saveexec_b64 s[50:51], s[46:47]
	v_mbcnt_lo_u32_b32 v18, s48, 0
	v_mbcnt_hi_u32_b32 v18, s49, v18
	v_cmp_gt_i32_e64 s[46:47], s54, v18
	s_and_b64 s[46:47], s[48:49], s[46:47]
	s_orn2_b64 s[52:53], s[46:47], exec
	s_or_b64 exec, exec, s[50:51]
	v_cndmask_b32_e64 v18, 0, 1, s[52:53]
	v_cmp_eq_u32_e64 s[66:67], 0, v16
	v_cmp_ne_u32_e64 s[50:51], 0, v18
	s_and_saveexec_b64 s[46:47], s[66:67]
	s_cbranch_execz .LBB0_1067
	v_mov_b64_e32 v[30:31], s[50:51]
	global_store_dwordx2 v[0:1], v[30:31], off

.LBB0_1176:
	v_lshlrev_b32_e64 v22, v21, 1
	v_or_b32_e32 v22, v22, v11
	s_waitcnt lgkmcnt(3)
	v_cmp_ge_u32_e32 vcc, v8, v22
	s_bcnt1_i32_b64 s0, vcc
	v_cmp_ge_u32_e32 vcc, v9, v22
	s_bcnt1_i32_b64 s1, vcc
	s_waitcnt lgkmcnt(2)
	v_cmp_ge_u32_e32 vcc, v6, v22
	s_add_i32 s0, s1, s0
	s_bcnt1_i32_b64 s1, vcc
	v_cmp_ge_u32_e32 vcc, v7, v22
	s_add_i32 s0, s0, s1
	s_bcnt1_i32_b64 s1, vcc
	s_waitcnt lgkmcnt(1)
	v_cmp_ge_u32_e32 vcc, v4, v22
	s_add_i32 s0, s0, s1
	s_bcnt1_i32_b64 s1, vcc
	v_cmp_ge_u32_e32 vcc, v5, v22
	s_add_i32 s0, s0, s1
	s_bcnt1_i32_b64 s1, vcc
	s_waitcnt lgkmcnt(0)
	v_cmp_ge_u32_e32 vcc, v2, v22
	s_add_i32 s0, s0, s1
	s_bcnt1_i32_b64 s1, vcc
	v_cmp_ge_u32_e32 vcc, v3, v22
	s_add_i32 s0, s0, s1
	s_bcnt1_i32_b64 s1, vcc
	v_cmp_ge_u32_e32 vcc, v20, v22
	s_add_i32 s0, s0, s1
	s_bcnt1_i32_b64 s1, vcc
	v_cmp_ge_u32_e32 vcc, v19, v22
	s_add_i32 s0, s0, s1
	s_bcnt1_i32_b64 s1, vcc
	v_cmp_ge_u32_e32 vcc, v18, v22
	s_add_i32 s0, s0, s1
	s_bcnt1_i32_b64 s1, vcc
	v_cmp_ge_u32_e32 vcc, v15, v22
	s_add_i32 s0, s0, s1
	s_bcnt1_i32_b64 s1, vcc
	v_cmp_ge_u32_e32 vcc, v14, v22
	s_add_i32 s0, s0, s1
	s_bcnt1_i32_b64 s1, vcc
	v_cmp_ge_u32_e32 vcc, v13, v22
	s_add_i32 s0, s0, s1
	s_bcnt1_i32_b64 s1, vcc
	v_cmp_ge_u32_e32 vcc, v12, v22
	s_add_i32 s0, s0, s1
	s_bcnt1_i32_b64 s1, vcc
	v_cmp_ge_u32_e32 vcc, v10, v22
	s_add_i32 s0, s0, s1
	s_bcnt1_i32_b64 s1, vcc
	s_add_i32 s2, s0, s1
	s_cmpk_eq_i32 s2, 0x100
	s_cselect_b64 s[0:1], -1, 0
	s_cmpk_lt_u32 s2, 0x100
	s_cselect_b64 vcc, -1, 0
	v_cndmask_b32_e32 v11, v22, v11, vcc
	v_subrev_co_u32_e32 v21, vcc, 1, v21
	s_or_b64 s[0:1], s[0:1], vcc
	s_andn2_b64 vcc, exec, s[0:1]
	s_cbranch_vccnz .LBB0_1176
	s_cmpk_eq_i32 s2, 0x100
	s_cbranch_scc1 .Lselfast_16
	v_cmp_gt_u32_e32 vcc, v8, v11
	s_bcnt1_i32_b64 s34, vcc
	v_cmp_gt_u32_e32 vcc, v9, v11
	s_bcnt1_i32_b64 s35, vcc
	v_cmp_gt_u32_e32 vcc, v6, v11
	v_cmp_gt_u32_e64 s[28:29], v10, v11
	s_bcnt1_i32_b64 s36, vcc
	v_cmp_gt_u32_e32 vcc, v7, v11
	s_bcnt1_i32_b64 s28, s[28:29]
	s_add_i32 s29, s34, s35
	s_bcnt1_i32_b64 s37, vcc
	v_cmp_gt_u32_e32 vcc, v4, v11
	s_add_i32 s29, s29, s36
	s_bcnt1_i32_b64 s38, vcc
	v_cmp_gt_u32_e32 vcc, v5, v11
	s_add_i32 s29, s29, s37
	s_bcnt1_i32_b64 s39, vcc
	v_cmp_gt_u32_e32 vcc, v2, v11
	s_add_i32 s29, s29, s38
	s_bcnt1_i32_b64 s40, vcc
	v_cmp_gt_u32_e32 vcc, v3, v11
	s_add_i32 s29, s29, s39
	s_bcnt1_i32_b64 s41, vcc
	v_cmp_gt_u32_e32 vcc, v20, v11
	s_add_i32 s29, s29, s40
	s_bcnt1_i32_b64 s42, vcc
	v_cmp_gt_u32_e32 vcc, v19, v11
	s_add_i32 s29, s29, s41
	s_bcnt1_i32_b64 s43, vcc
	v_cmp_gt_u32_e32 vcc, v18, v11
	s_add_i32 s29, s29, s42
	s_bcnt1_i32_b64 s44, vcc
	v_cmp_gt_u32_e32 vcc, v15, v11
	s_add_i32 s29, s29, s43
	s_bcnt1_i32_b64 s45, vcc
	v_cmp_gt_u32_e32 vcc, v14, v11
	s_add_i32 s29, s29, s44
	s_bcnt1_i32_b64 s46, vcc
	v_cmp_gt_u32_e32 vcc, v13, v11
	s_add_i32 s29, s29, s45
	s_bcnt1_i32_b64 s47, vcc
	v_cmp_gt_u32_e32 vcc, v12, v11
	s_add_i32 s29, s29, s46
	s_bcnt1_i32_b64 s48, vcc
	s_add_i32 s29, s29, s47
	s_add_i32 s29, s29, s48
	s_add_i32 s29, s29, s28
	v_cmp_le_u32_e64 s[30:31], v8, v11
	v_cmp_le_u32_e64 s[26:27], v9, v11
	v_cmp_le_u32_e64 s[24:25], v6, v11
	v_cmp_le_u32_e64 s[22:23], v7, v11
	v_cmp_le_u32_e64 s[20:21], v4, v11
	v_cmp_le_u32_e64 s[18:19], v5, v11
	v_cmp_le_u32_e64 s[16:17], v2, v11
	v_cmp_le_u32_e64 s[14:15], v3, v11
	v_cmp_le_u32_e64 s[12:13], v20, v11
	v_cmp_le_u32_e64 s[10:11], v19, v11
	v_cmp_le_u32_e64 s[8:9], v18, v11
	v_cmp_le_u32_e64 s[6:7], v15, v11
	v_cmp_le_u32_e64 s[4:5], v14, v11
	v_cmp_le_u32_e64 s[2:3], v13, v11
	v_cmp_le_u32_e64 s[0:1], v12, v11
	v_cmp_le_u32_e32 vcc, v10, v11
	s_sub_i32 s38, 0x100, s29
	v_cmp_eq_u32_e64 s[28:29], v8, v11
	s_mov_b64 s[36:37], -1
	s_and_saveexec_b64 s[34:35], s[30:31]
	v_mbcnt_lo_u32_b32 v8, s28, 0
	v_mbcnt_hi_u32_b32 v8, s29, v8
	v_cmp_gt_i32_e64 s[30:31], s38, v8
	s_and_b64 s[30:31], s[28:29], s[30:31]
	s_orn2_b64 s[36:37], s[30:31], exec
	s_or_b64 exec, exec, s[34:35]
	v_cndmask_b32_e64 v8, 0, 1, s[36:37]
	v_cmp_eq_u32_e64 s[66:67], 0, v16
	v_cmp_ne_u32_e64 s[34:35], 0, v8
	s_and_saveexec_b64 s[30:31], s[66:67]
	s_cbranch_execz .LBB0_1181
	v_mov_b64_e32 v[22:23], s[34:35]
	global_store_dwordx2 v[0:1], v[22:23], off

.LBB0_1257:
	v_lshlrev_b32_e64 v12, v11, 1
	v_or_b32_e32 v12, v12, v4
	s_waitcnt lgkmcnt(0)
	v_cmp_ge_u32_e32 vcc, v10, v12
	s_bcnt1_i32_b64 s0, vcc
	v_cmp_ge_u32_e32 vcc, v9, v12
	s_bcnt1_i32_b64 s1, vcc
	v_cmp_ge_u32_e32 vcc, v8, v12
	s_add_i32 s0, s1, s0
	s_bcnt1_i32_b64 s1, vcc
	v_cmp_ge_u32_e32 vcc, v7, v12
	s_add_i32 s0, s0, s1
	s_bcnt1_i32_b64 s1, vcc
	v_cmp_ge_u32_e32 vcc, v6, v12
	s_add_i32 s0, s0, s1
	s_bcnt1_i32_b64 s1, vcc
	v_cmp_ge_u32_e32 vcc, v5, v12
	s_add_i32 s0, s0, s1
	s_bcnt1_i32_b64 s1, vcc
	v_cmp_ge_u32_e32 vcc, v3, v12
	s_add_i32 s0, s0, s1
	s_bcnt1_i32_b64 s1, vcc
	v_cmp_ge_u32_e32 vcc, v2, v12
	s_add_i32 s0, s0, s1
	s_bcnt1_i32_b64 s1, vcc
	s_add_i32 s2, s0, s1
	s_cmpk_eq_i32 s2, 0x100
	s_cselect_b64 s[0:1], -1, 0
	s_cmpk_lt_u32 s2, 0x100
	s_cselect_b64 vcc, -1, 0
	v_cndmask_b32_e32 v4, v12, v4, vcc
	v_subrev_co_u32_e32 v11, vcc, 1, v11
	s_or_b64 s[0:1], s[0:1], vcc
	s_andn2_b64 vcc, exec, s[0:1]
	s_cbranch_vccnz .LBB0_1257
	s_cmpk_eq_i32 s2, 0x100
	s_cbranch_scc1 .Lselfast_8

.LBB0_1662:
	s_or_b64 exec, exec, s[0:1]
	s_waitcnt lgkmcnt(0)
	s_barrier
	s_load_dwordx2 s[34:35], s[60:61], 0x1d0
	s_waitcnt lgkmcnt(0)
	s_barrier
	s_mov_b64 s[0:1], exec
	v_readlane_b32 s2, v253, 2
	v_readlane_b32 s3, v253, 3
	s_and_b64 s[2:3], s[0:1], s[2:3]
	s_mov_b64 exec, s[2:3]
	s_cbranch_execz .LBB0_1666
	s_mov_b64 s[4:5], exec
	v_mbcnt_lo_u32_b32 v0, s4, 0
	v_mbcnt_hi_u32_b32 v0, s5, v0
	v_cmp_eq_u32_e32 vcc, 0, v0
	s_and_saveexec_b64 s[2:3], vcc
	s_cbranch_execz .LBB0_1665
	s_bcnt1_i32_b64 s4, s[4:5]
	v_readlane_b32 s101, v253, 14
	s_nop 1
	s_cmp_lt_u32 s101, 48
	s_cselect_b32 s4, 0, s4
	v_mov_b32_e32 v1, 0
	v_mov_b32_e32 v2, s4
	global_atomic_add v1, v1, v2, s[34:35] offset:256 sc0

.LBB0_1666:
	s_or_b64 exec, exec, s[0:1]
	v_mov_b32_e32 v84, 0x20810
	s_waitcnt lgkmcnt(0)
	s_barrier
	ds_read_b32 v0, v84
	s_movk_i32 s0, 0x5ff
	s_waitcnt lgkmcnt(0)
	v_cmp_lt_i32_e32 vcc, s0, v0
	v_readfirstlane_b32 s6, v0
	s_cbranch_vccnz .LBB0_1730
	v_readlane_b32 s101, v253, 14
	s_nop 1
	s_add_i32 s6, s6, 48
	s_cmp_lt_u32 s101, 48
	s_cselect_b32 s6, s101, s6
	s_load_dwordx8 s[36:43], s[60:61], 0x198
	s_load_dwordx8 s[44:51], s[60:61], 0xe0
	s_load_dwordx8 s[52:59], s[60:61], 0x148
	s_load_dwordx4 s[28:31], s[60:61], 0x28
	v_and_b32_e32 v0, 64, v133
	s_waitcnt lgkmcnt(0)
	s_add_u32 s33, s36, 8
	s_addc_u32 s68, s37, 0
	s_add_u32 s69, s38, 8
	s_mov_b32 s61, 0
	s_addc_u32 s70, s39, 0
	v_mov_b32_e32 v65, 0
	s_movk_i32 s71, 0x300
	s_movk_i32 s72, 0xffc0
	s_movk_i32 s73, 0x80
	s_movk_i32 s74, 0x100
	s_movk_i32 s75, 0xa0
	s_mov_b32 s76, 0x10000
	s_mov_b32 s77, 0x20000
	s_mov_b32 s78, 0x40000
	s_mov_b32 s79, 0x80000
	s_mov_b32 s80, 0xff800000
	s_movk_i32 s81, 0x600
	s_movk_i32 s82, 0x210
	v_mov_b32_e32 v85, 0x7f
	v_mov_b32_e32 v86, 0xff800000
	v_xor_b32_e32 v87, 16, v133
	v_add_u32_e32 v88, 64, v0
	v_xor_b32_e32 v89, 32, v133
	v_mov_b32_e32 v90, 0x41
	s_branch .LBB0_1669
.LBB0_1668:
	s_or_b64 exec, exec, s[0:1]
	s_waitcnt lgkmcnt(0)
	s_barrier
	ds_read_b32 v0, v84
	s_movk_i32 s0, 0x600
	s_waitcnt lgkmcnt(0)
	v_cmp_gt_i32_e32 vcc, s0, v0
	v_readfirstlane_b32 s6, v0
	s_cbranch_vccz .LBB0_1729
	s_nop 1
	s_add_i32 s6, s6, 48
.LBB0_1669:
	v_mov_b32_e32 v91, 0
	s_mov_b64 s[0:1], exec
	s_cmp_lt_u32 s6, 48
	s_cbranch_scc1 .LBB0_1673
	v_readlane_b32 s2, v253, 2
	v_readlane_b32 s3, v253, 3
	s_and_b64 s[2:3], s[0:1], s[2:3]
	s_mov_b64 exec, s[2:3]
	s_cbranch_execz .LBB0_1673
	s_mov_b64 s[4:5], exec
	v_mbcnt_lo_u32_b32 v0, s4, 0
	v_mbcnt_hi_u32_b32 v0, s5, v0
	v_cmp_eq_u32_e32 vcc, 0, v0
	s_and_saveexec_b64 s[2:3], vcc
	s_cbranch_execz .LBB0_1672
	s_bcnt1_i32_b64 s4, s[4:5]
	v_mov_b32_e32 v1, s4
	global_atomic_add v1, v65, v1, s[34:35] offset:256 sc0

.LBB0_1680:
	s_add_i32 s92, s88, -2
	s_cmp_lt_u32 s92, s85
	s_cselect_b64 s[64:65], -1, 0
	s_cmp_ge_u32 s92, s85
	s_waitcnt vmcnt(2)
	v_mov_b64_e32 v[70:71], v[68:69]
	s_cbranch_scc1 .LBB0_1682
	global_load_dwordx2 v[70:71], v[66:67], off

.Lp3a_noload:
	s_waitcnt vmcnt(0)
	s_branch .LBB0_1680

.LBB0_1706:
	s_cmp_lt_u32 s60, 63
	s_cselect_b64 s[24:25], -1, 0
	s_cmp_gt_u32 s60, 62
	s_cselect_b64 s[22:23], -1, 0
	s_and_b64 vcc, exec, s[22:23]
	ds_write_b128 v76, v[56:59]
	ds_write_b128 v76, v[60:63] offset:10240
	s_waitcnt lgkmcnt(0)
	s_barrier
	s_cbranch_vccnz .LBB0_1712
	s_waitcnt vmcnt(7)
	v_subrev_u32_e32 v16, 64, v103
	v_min_i32_e32 v16, 0x101f, v16
	s_movk_i32 s0, 0x180
	v_mad_i64_i32 v[82:83], s[0:1], v16, s0, 0
	s_cmp_eq_u32 s60, 62
	s_mov_b64 s[0:1], -1
	s_cbranch_scc1 .LBB0_1709
	v_lshlrev_b64 v[16:17], 2, v[82:83]
	v_lshl_add_u64 v[18:19], v[68:69], 0, v[16:17]
	s_waitcnt vmcnt(5)
	v_lshl_add_u64 v[28:29], v[70:71], 0, v[16:17]
	global_load_dwordx4 v[8:11], v[18:19], off offset:16
	s_nop 0
	global_load_dwordx4 v[16:19], v[18:19], off
	s_nop 0
	global_load_dwordx4 v[12:15], v[28:29], off offset:16
	s_nop 0
	global_load_dwordx4 v[28:31], v[28:29], off
	s_mov_b64 s[0:1], 0
	s_waitcnt vmcnt(4)
	s_add_i32 s64, s60, 1
	s_cmpk_lt_u32 s64, 0x41
	s_cselect_b64 s[26:27], -1, 0
	s_cmp_gt_u32 s64, 64
	v_mov_b64_e32 v[56:57], v[80:81]
	s_cbranch_scc0 .LBB0_1718
	s_branch .Lp3s_1713

.Lp3s_1713:
	v_cmp_lt_u32_e32 vcc, s60, v67
	s_and_b64 s[0:1], s[10:11], vcc
	s_and_saveexec_b64 s[62:63], s[0:1]
	s_cbranch_execnz .LBB0_1719

.LBB0_1726:
	s_or_b64 exec, exec, s[0:1]
	s_mov_b64 s[0:1], exec
	v_readlane_b32 s2, v253, 2
	v_readlane_b32 s3, v253, 3
	s_and_b64 s[2:3], s[0:1], s[2:3]
	s_mov_b64 exec, s[2:3]
	s_cbranch_execz .Lp3_late_done
	s_mov_b64 s[4:5], exec
	v_mbcnt_lo_u32_b32 v0, s4, 0
	v_mbcnt_hi_u32_b32 v0, s5, v0
	v_cmp_eq_u32_e32 vcc, 0, v0
	s_and_saveexec_b64 s[2:3], vcc
	s_cbranch_execz .Lp3_late_a
	s_bcnt1_i32_b64 s4, s[4:5]
	v_mov_b32_e32 v1, s4
	global_atomic_add v1, v65, v1, s[34:35] offset:256 sc0

.LBB0_1787:
	v_add_u32_e32 v128, v141, v142
	v_add_u32_e32 v171, v144, v143
	ds_read_b128 v[172:175], v128
	ds_read_b128 v[176:179], v164 offset:32768
	ds_read_b128 v[180:183], v164 offset:34816
	ds_read_b128 v[184:187], v171
	ds_read_b128 v[188:191], v164 offset:36864
	ds_read_b128 v[192:195], v164 offset:38912
	s_waitcnt lgkmcnt(0)
	v_mfma_f32_16x16x32_bf16 v[4:7], v[172:175], v[176:179], v[4:7]
	s_add_i32 s1, s1, 2
	v_mfma_f32_16x16x32_bf16 v[8:11], v[172:175], v[180:183], v[8:11]
	v_mfma_f32_16x16x32_bf16 v[12:15], v[172:175], v[188:191], v[12:15]
	v_mfma_f32_16x16x32_bf16 v[16:19], v[172:175], v[192:195], v[16:19]
	v_mfma_f32_16x16x32_bf16 v[20:23], v[184:187], v[176:179], v[20:23]
	v_mfma_f32_16x16x32_bf16 v[24:27], v[184:187], v[180:183], v[24:27]
	v_mfma_f32_16x16x32_bf16 v[28:31], v[184:187], v[188:191], v[28:31]
	v_mfma_f32_16x16x32_bf16 v[32:35], v[184:187], v[192:195], v[32:35]
	ds_read_b128 v[172:175], v165
	ds_read_b128 v[184:187], v166
	s_waitcnt lgkmcnt(0)
	v_mfma_f32_16x16x32_bf16 v[36:39], v[172:175], v[176:179], v[36:39]
	v_mfma_f32_16x16x32_bf16 v[40:43], v[172:175], v[180:183], v[40:43]
	v_mfma_f32_16x16x32_bf16 v[44:47], v[172:175], v[188:191], v[44:47]
	v_mfma_f32_16x16x32_bf16 v[48:51], v[172:175], v[192:195], v[48:51]
	v_mfma_f32_16x16x32_bf16 v[52:55], v[184:187], v[176:179], v[52:55]
	v_mfma_f32_16x16x32_bf16 v[56:59], v[184:187], v[180:183], v[56:59]
	v_mfma_f32_16x16x32_bf16 v[60:63], v[184:187], v[188:191], v[60:63]
	v_mfma_f32_16x16x32_bf16 v[64:67], v[184:187], v[192:195], v[64:67]
	ds_read_b128 v[172:175], v167
	ds_read_b128 v[184:187], v168
	s_waitcnt lgkmcnt(0)
	v_mfma_f32_16x16x32_bf16 v[196:199], v[172:175], v[176:179], v[68:71]
	v_mfma_f32_16x16x32_bf16 v[200:203], v[172:175], v[180:183], v[72:75]
	s_nop 1
	ds_read_b128 v[68:71], v169
	ds_read_b128 v[72:75], v170
	s_waitcnt lgkmcnt(0)
	v_mfma_f32_16x16x32_bf16 v[0:3], v[72:75], v[192:195], v[0:3]
	v_mfma_f32_16x16x32_bf16 v[204:207], v[172:175], v[188:191], v[76:79]
	v_mfma_f32_16x16x32_bf16 v[172:175], v[172:175], v[192:195], v[80:83]
	v_mfma_f32_16x16x32_bf16 v[208:211], v[184:187], v[176:179], v[84:87]
	v_mfma_f32_16x16x32_bf16 v[212:215], v[184:187], v[180:183], v[88:91]
	v_mfma_f32_16x16x32_bf16 v[216:219], v[184:187], v[188:191], v[92:95]
	v_mfma_f32_16x16x32_bf16 v[184:187], v[184:187], v[192:195], v[96:99]
	v_mfma_f32_16x16x32_bf16 v[220:223], v[68:71], v[176:179], v[100:103]
	v_mfma_f32_16x16x32_bf16 v[224:227], v[68:71], v[180:183], v[104:107]
	v_mfma_f32_16x16x32_bf16 v[228:231], v[68:71], v[188:191], v[108:111]
	v_mfma_f32_16x16x32_bf16 v[232:235], v[68:71], v[192:195], v[112:115]
	v_mfma_f32_16x16x32_bf16 v[176:179], v[72:75], v[176:179], v[116:119]
	v_mfma_f32_16x16x32_bf16 v[180:183], v[72:75], v[180:183], v[120:123]
	v_mfma_f32_16x16x32_bf16 v[188:191], v[72:75], v[188:191], v[124:127]
	ds_read_b128 v[68:71], v128 offset:1024
	ds_read_b128 v[192:195], v164 offset:33792
	ds_read_b128 v[236:239], v164 offset:35840
	ds_read_b128 v[72:75], v171 offset:1024
	s_waitcnt lgkmcnt(2)
	v_mfma_f32_16x16x32_bf16 v[124:127], v[68:71], v[192:195], v[4:7]
	s_nop 2
	ds_read_b128 v[4:7], v164 offset:37888
	ds_read_b128 v[240:243], v164 offset:39936
	s_waitcnt lgkmcnt(3)
	v_mfma_f32_16x16x32_bf16 v[120:123], v[68:71], v[236:239], v[8:11]
	s_waitcnt lgkmcnt(1)
	v_mfma_f32_16x16x32_bf16 v[116:119], v[68:71], v[4:7], v[12:15]
	s_nop 0
	ds_read_b128 v[8:11], v165 offset:1024
	s_nop 0
	ds_read_b128 v[12:15], v166 offset:1024
	s_waitcnt lgkmcnt(2)
	v_mfma_f32_16x16x32_bf16 v[112:115], v[68:71], v[240:243], v[16:19]
	v_mfma_f32_16x16x32_bf16 v[108:111], v[72:75], v[192:195], v[20:23]
	v_mfma_f32_16x16x32_bf16 v[104:107], v[72:75], v[236:239], v[24:27]
	v_mfma_f32_16x16x32_bf16 v[100:103], v[72:75], v[4:7], v[28:31]
	v_mfma_f32_16x16x32_bf16 v[96:99], v[72:75], v[240:243], v[32:35]
	s_waitcnt lgkmcnt(1)
	v_mfma_f32_16x16x32_bf16 v[92:95], v[8:11], v[192:195], v[36:39]
	v_mfma_f32_16x16x32_bf16 v[88:91], v[8:11], v[236:239], v[40:43]
	v_mfma_f32_16x16x32_bf16 v[84:87], v[8:11], v[4:7], v[44:47]
	v_mfma_f32_16x16x32_bf16 v[80:83], v[8:11], v[240:243], v[48:51]
	s_waitcnt lgkmcnt(0)
	v_mfma_f32_16x16x32_bf16 v[76:79], v[12:15], v[192:195], v[52:55]
	v_mfma_f32_16x16x32_bf16 v[72:75], v[12:15], v[236:239], v[56:59]
	v_mfma_f32_16x16x32_bf16 v[68:71], v[12:15], v[4:7], v[60:63]
	v_mfma_f32_16x16x32_bf16 v[64:67], v[12:15], v[240:243], v[64:67]
	ds_read_b128 v[8:11], v167 offset:1024
	ds_read_b128 v[12:15], v168 offset:1024
	s_waitcnt lgkmcnt(1)
	v_mfma_f32_16x16x32_bf16 v[60:63], v[8:11], v[192:195], v[196:199]
	v_mfma_f32_16x16x32_bf16 v[56:59], v[8:11], v[236:239], v[200:203]
	v_mfma_f32_16x16x32_bf16 v[52:55], v[8:11], v[4:7], v[204:207]
	v_mfma_f32_16x16x32_bf16 v[48:51], v[8:11], v[240:243], v[172:175]
	ds_read_b128 v[8:11], v169 offset:1024
	s_nop 1
	ds_read_b128 v[172:175], v170 offset:1024
	s_waitcnt lgkmcnt(2)
	v_mfma_f32_16x16x32_bf16 v[44:47], v[12:15], v[192:195], v[208:211]
	v_mfma_f32_16x16x32_bf16 v[40:43], v[12:15], v[236:239], v[212:215]
	v_mfma_f32_16x16x32_bf16 v[36:39], v[12:15], v[4:7], v[216:219]
	v_mfma_f32_16x16x32_bf16 v[32:35], v[12:15], v[240:243], v[184:187]
	s_waitcnt lgkmcnt(1)
	v_mfma_f32_16x16x32_bf16 v[28:31], v[8:11], v[192:195], v[220:223]
	v_mfma_f32_16x16x32_bf16 v[24:27], v[8:11], v[236:239], v[224:227]
	v_mfma_f32_16x16x32_bf16 v[20:23], v[8:11], v[4:7], v[228:231]
	v_mfma_f32_16x16x32_bf16 v[16:19], v[8:11], v[240:243], v[232:235]
	s_waitcnt lgkmcnt(0)
	v_mfma_f32_16x16x32_bf16 v[12:15], v[172:175], v[192:195], v[176:179]
	v_mfma_f32_16x16x32_bf16 v[8:11], v[172:175], v[236:239], v[180:183]
	v_mfma_f32_16x16x32_bf16 v[4:7], v[172:175], v[4:7], v[188:191]
	v_mfma_f32_16x16x32_bf16 v[0:3], v[172:175], v[240:243], v[0:3]
	s_waitcnt vmcnt(0)
	s_add_u32 s28, s28, 0x100
	s_addc_u32 s29, s29, 0
	s_andn2_b64 vcc, exec, s[30:31]
	s_barrier
	s_cbranch_vccz .LBB0_1790
.LBB0_1788:
	v_mov_b32_e32 v128, v130
	ds_read_b128 v[172:175], v156
	ds_read_b128 v[176:179], v155 offset:32768
	ds_read_b128 v[180:183], v155 offset:34816
	ds_read_b128 v[184:187], v157
	ds_read_b128 v[188:191], v155 offset:36864
	ds_read_b128 v[192:195], v155 offset:38912
	v_lshlrev_b32_e32 v196, 9, v128
	v_lshlrev_b32_e32 v171, 4, v128
	v_and_b32_e32 v228, 32, v128
	v_and_b32_e32 v232, 0x7800, v196
	v_bfe_i32 v196, v128, 6, 22
	v_bfe_u32 v128, v128, 27, 1
	v_add_u32_e32 v128, v196, v128
	v_lshrrev_b32_e32 v128, 1, v128
	v_and_b32_e32 v229, 48, v171
	v_mul_i32_i24_e32 v128, 0x7f80, v128
	s_waitcnt lgkmcnt(4)
	v_mfma_f32_16x16x32_bf16 v[124:127], v[172:175], v[176:179], v[124:127]
	v_bitop3_b32 v128, v229, v128, v228 bitop3:0xde
	v_readfirstlane_b32 s30, v145
	s_mov_b32 m0, s30
	s_waitcnt lgkmcnt(3)
	v_mfma_f32_16x16x32_bf16 v[120:123], v[172:175], v[180:183], v[120:123]
	v_readfirstlane_b32 s30, v146
	s_waitcnt lgkmcnt(1)
	v_mfma_f32_16x16x32_bf16 v[116:119], v[172:175], v[188:191], v[116:119]
	s_waitcnt lgkmcnt(0)
	v_mfma_f32_16x16x32_bf16 v[112:115], v[172:175], v[192:195], v[112:115]
	v_lshlrev_b32_e32 v172, 6, v196
	v_add3_u32 v128, v128, v232, v172
	ds_read_b128 v[172:175], v158
	v_lshl_add_u64 v[196:197], s[28:29], 0, v[128:129]
	v_lshl_add_u64 v[198:199], s[24:25], 0, v[196:197]
	v_lshl_add_u64 v[198:199], v[198:199], 0, s[20:21]
	v_lshl_add_u64 v[196:197], s[26:27], 0, v[196:197]
	v_add_u32_e32 v128, 0x2000, v171
	global_load_lds_dwordx4 v[198:199], off
	v_lshl_add_u64 v[196:197], v[196:197], 0, s[20:21]
	s_mov_b32 m0, s30
	v_ashrrev_i32_e32 v128, 10, v128
	global_load_lds_dwordx4 v[196:197], off
	v_lshrrev_b32_e32 v196, 31, v128
	v_add_u32_e32 v196, v128, v196
	v_mfma_f32_16x16x32_bf16 v[108:111], v[184:187], v[176:179], v[108:111]
	v_lshlrev_b32_e32 v128, 6, v128
	v_readfirstlane_b32 s30, v147
	s_mov_b32 m0, s30
	v_mfma_f32_16x16x32_bf16 v[104:107], v[184:187], v[180:183], v[104:107]
	v_readfirstlane_b32 s30, v150
	v_mfma_f32_16x16x32_bf16 v[100:103], v[184:187], v[188:191], v[100:103]
	v_mfma_f32_16x16x32_bf16 v[96:99], v[184:187], v[192:195], v[96:99]
	ds_read_b128 v[184:187], v159
	s_waitcnt lgkmcnt(0)
	v_mfma_f32_16x16x32_bf16 v[92:95], v[172:175], v[176:179], v[92:95]
	v_mfma_f32_16x16x32_bf16 v[88:91], v[172:175], v[180:183], v[88:91]
	v_mfma_f32_16x16x32_bf16 v[84:87], v[172:175], v[188:191], v[84:87]
	v_mfma_f32_16x16x32_bf16 v[80:83], v[172:175], v[192:195], v[80:83]
	v_lshrrev_b32_e32 v172, 1, v196
	v_mul_lo_u32 v172, v172, s36
	v_bitop3_b32 v172, v229, v172, v228 bitop3:0xde
	v_add3_u32 v128, v172, v232, v128
	v_lshl_add_u64 v[196:197], s[28:29], 0, v[128:129]
	v_lshl_add_u64 v[172:173], s[24:25], 0, v[196:197]
	v_lshl_add_u64 v[198:199], v[172:173], 0, s[20:21]
	ds_read_b128 v[172:175], v160
	v_mfma_f32_16x16x32_bf16 v[76:79], v[184:187], v[176:179], v[76:79]
	v_lshl_add_u64 v[196:197], s[26:27], 0, v[196:197]
	global_load_lds_dwordx4 v[198:199], off
	v_mfma_f32_16x16x32_bf16 v[72:75], v[184:187], v[180:183], v[72:75]
	v_lshl_add_u64 v[200:201], v[196:197], 0, s[20:21]
	s_mov_b32 m0, s30
	v_readfirstlane_b32 s30, v151
	v_mfma_f32_16x16x32_bf16 v[68:71], v[184:187], v[188:191], v[68:71]
	global_load_lds_dwordx4 v[200:201], off
	s_mov_b32 m0, s30
	v_mfma_f32_16x16x32_bf16 v[64:67], v[184:187], v[192:195], v[64:67]
	ds_read_b128 v[184:187], v161
	v_readfirstlane_b32 s30, v152
	s_waitcnt lgkmcnt(0)
	v_mfma_f32_16x16x32_bf16 v[196:199], v[172:175], v[176:179], v[60:63]
	s_nop 2
	v_add_u32_e32 v60, 0x4000, v171
	v_mfma_f32_16x16x32_bf16 v[200:203], v[172:175], v[180:183], v[56:59]
	s_nop 2
	v_ashrrev_i32_e32 v56, 10, v60
	v_lshrrev_b32_e32 v57, 31, v56
	v_add_u32_e32 v57, v56, v57
	v_mfma_f32_16x16x32_bf16 v[204:207], v[172:175], v[188:191], v[52:55]
	s_nop 2
	v_lshrrev_b32_e32 v52, 1, v57
	v_mfma_f32_16x16x32_bf16 v[216:219], v[184:187], v[188:191], v[36:39]
	v_mul_lo_u32 v52, v52, s36
	v_bitop3_b32 v52, v229, v52, v228 bitop3:0xde
	s_nop 0
	ds_read_b128 v[36:39], v162
	v_mfma_f32_16x16x32_bf16 v[172:175], v[172:175], v[192:195], v[48:51]
	s_nop 2
	v_lshlrev_b32_e32 v48, 6, v56
	v_add3_u32 v128, v52, v232, v48
	v_lshl_add_u64 v[48:49], s[28:29], 0, v[128:129]
	v_mfma_f32_16x16x32_bf16 v[208:211], v[184:187], v[176:179], v[44:47]
	s_nop 2
	v_lshl_add_u64 v[44:45], s[24:25], 0, v[48:49]
	v_lshl_add_u64 v[44:45], v[44:45], 0, s[20:21]
	v_mfma_f32_16x16x32_bf16 v[212:215], v[184:187], v[180:183], v[40:43]
	global_load_lds_dwordx4 v[44:45], off
	s_mov_b32 m0, s30
	s_nop 0
	v_lshl_add_u64 v[40:41], s[26:27], 0, v[48:49]
	v_lshl_add_u64 v[40:41], v[40:41], 0, s[20:21]
	global_load_lds_dwordx4 v[40:41], off
	v_add_u32_e32 v40, 0x6000, v171
	v_mfma_f32_16x16x32_bf16 v[184:187], v[184:187], v[192:195], v[32:35]
	v_readfirstlane_b32 s30, v153
	s_mov_b32 m0, s30
	v_readfirstlane_b32 s30, v154
	ds_read_b128 v[32:35], v163
	s_waitcnt lgkmcnt(0)
	v_mfma_f32_16x16x32_bf16 v[220:223], v[36:39], v[176:179], v[28:31]
	s_nop 2
	v_ashrrev_i32_e32 v28, 10, v40
	v_lshrrev_b32_e32 v29, 31, v28
	v_add_u32_e32 v29, v28, v29
	v_mfma_f32_16x16x32_bf16 v[224:227], v[36:39], v[180:183], v[24:27]
	s_nop 2
	v_lshrrev_b32_e32 v24, 1, v29
	v_mul_lo_u32 v24, v24, s36
	v_bitop3_b32 v24, v229, v24, v228 bitop3:0xde
	v_mfma_f32_16x16x32_bf16 v[228:231], v[36:39], v[188:191], v[20:23]
	s_nop 2
	v_lshlrev_b32_e32 v20, 6, v28
	v_add3_u32 v128, v24, v232, v20
	v_lshl_add_u64 v[20:21], s[28:29], 0, v[128:129]
	v_mfma_f32_16x16x32_bf16 v[232:235], v[36:39], v[192:195], v[16:19]
	s_nop 2
	v_lshl_add_u64 v[16:17], s[24:25], 0, v[20:21]
	v_lshl_add_u64 v[16:17], v[16:17], 0, s[20:21]
	v_mfma_f32_16x16x32_bf16 v[180:183], v[32:35], v[180:183], v[8:11]
	global_load_lds_dwordx4 v[16:17], off
	s_mov_b32 m0, s30
	s_nop 0
	v_lshl_add_u64 v[8:9], s[26:27], 0, v[20:21]
	v_lshl_add_u64 v[8:9], v[8:9], 0, s[20:21]
	global_load_lds_dwordx4 v[8:9], off
	v_mfma_f32_16x16x32_bf16 v[0:3], v[32:35], v[192:195], v[0:3]
	v_mfma_f32_16x16x32_bf16 v[176:179], v[32:35], v[176:179], v[12:15]
	v_mfma_f32_16x16x32_bf16 v[188:191], v[32:35], v[188:191], v[4:7]
	ds_read_b128 v[16:19], v156 offset:1024
	ds_read_b128 v[192:195], v155 offset:33792
	ds_read_b128 v[236:239], v155 offset:35840
	ds_read_b128 v[32:35], v157 offset:1024
	s_waitcnt lgkmcnt(0)
	v_mfma_f32_16x16x32_bf16 v[4:7], v[16:19], v[192:195], v[124:127]
	s_nop 2
	ds_read_b128 v[124:127], v155 offset:37888
	ds_read_b128 v[240:243], v155 offset:39936
	v_mfma_f32_16x16x32_bf16 v[20:23], v[32:35], v[192:195], v[108:111]
	v_mfma_f32_16x16x32_bf16 v[24:27], v[32:35], v[236:239], v[104:107]
	s_waitcnt lgkmcnt(1)
	v_mfma_f32_16x16x32_bf16 v[28:31], v[32:35], v[124:127], v[100:103]
	s_waitcnt lgkmcnt(0)
	v_mfma_f32_16x16x32_bf16 v[32:35], v[32:35], v[240:243], v[96:99]
	ds_read_b128 v[48:51], v158 offset:1024
	s_nop 1
	ds_read_b128 v[96:99], v159 offset:1024
	s_waitcnt lgkmcnt(1)
	v_mfma_f32_16x16x32_bf16 v[36:39], v[48:51], v[192:195], v[92:95]
	v_mfma_f32_16x16x32_bf16 v[40:43], v[48:51], v[236:239], v[88:91]
	v_mfma_f32_16x16x32_bf16 v[44:47], v[48:51], v[124:127], v[84:87]
	v_mfma_f32_16x16x32_bf16 v[48:51], v[48:51], v[240:243], v[80:83]
	s_waitcnt lgkmcnt(0)
	v_mfma_f32_16x16x32_bf16 v[52:55], v[96:99], v[192:195], v[76:79]
	v_mfma_f32_16x16x32_bf16 v[56:59], v[96:99], v[236:239], v[72:75]
	v_mfma_f32_16x16x32_bf16 v[60:63], v[96:99], v[124:127], v[68:71]
	v_mfma_f32_16x16x32_bf16 v[64:67], v[96:99], v[240:243], v[64:67]
	ds_read_b128 v[80:83], v160 offset:1024
	ds_read_b128 v[96:99], v161 offset:1024
	v_mfma_f32_16x16x32_bf16 v[8:11], v[16:19], v[236:239], v[120:123]
	v_mfma_f32_16x16x32_bf16 v[12:15], v[16:19], v[124:127], v[116:119]
	v_mfma_f32_16x16x32_bf16 v[16:19], v[16:19], v[240:243], v[112:115]
	s_waitcnt lgkmcnt(1)
	v_mfma_f32_16x16x32_bf16 v[68:71], v[80:83], v[192:195], v[196:199]
	v_mfma_f32_16x16x32_bf16 v[72:75], v[80:83], v[236:239], v[200:203]
	v_mfma_f32_16x16x32_bf16 v[76:79], v[80:83], v[124:127], v[204:207]
	v_mfma_f32_16x16x32_bf16 v[80:83], v[80:83], v[240:243], v[172:175]
	ds_read_b128 v[112:115], v162 offset:1024
	s_nop 1
	ds_read_b128 v[172:175], v163 offset:1024
	s_waitcnt lgkmcnt(2)
	v_mfma_f32_16x16x32_bf16 v[84:87], v[96:99], v[192:195], v[208:211]
	v_mfma_f32_16x16x32_bf16 v[88:91], v[96:99], v[236:239], v[212:215]
	v_mfma_f32_16x16x32_bf16 v[92:95], v[96:99], v[124:127], v[216:219]
	v_mfma_f32_16x16x32_bf16 v[96:99], v[96:99], v[240:243], v[184:187]
	s_waitcnt lgkmcnt(1)
	v_mfma_f32_16x16x32_bf16 v[100:103], v[112:115], v[192:195], v[220:223]
	v_mfma_f32_16x16x32_bf16 v[104:107], v[112:115], v[236:239], v[224:227]
	v_mfma_f32_16x16x32_bf16 v[108:111], v[112:115], v[124:127], v[228:231]
	v_mfma_f32_16x16x32_bf16 v[112:115], v[112:115], v[240:243], v[232:235]
	s_waitcnt lgkmcnt(0)
	v_mfma_f32_16x16x32_bf16 v[116:119], v[172:175], v[192:195], v[176:179]
	v_mfma_f32_16x16x32_bf16 v[120:123], v[172:175], v[236:239], v[180:183]
	v_mfma_f32_16x16x32_bf16 v[124:127], v[172:175], v[124:127], v[188:191]
	v_mfma_f32_16x16x32_bf16 v[0:3], v[172:175], v[240:243], v[0:3]
	s_waitcnt vmcnt(0)
	s_cmp_gt_u32 s1, 13
	s_cselect_b64 s[30:31], -1, 0
	s_and_b64 vcc, exec, s[30:31]
	s_barrier
	s_cbranch_vccnz .LBB0_1787
	v_mov_b32_e32 v128, v130
	v_readfirstlane_b32 s45, v131
	v_lshlrev_b32_e32 v172, 9, v128
	v_lshlrev_b32_e32 v171, 4, v128
	v_and_b32_e32 v176, 32, v128
	v_and_b32_e32 v178, 0x7800, v172
	v_bfe_i32 v172, v128, 6, 22
	v_bfe_u32 v128, v128, 27, 1
	v_add_u32_e32 v128, v172, v128
	v_lshrrev_b32_e32 v128, 1, v128
	v_and_b32_e32 v177, 48, v171
	v_mul_i32_i24_e32 v128, 0x7f80, v128
	v_bitop3_b32 v128, v177, v128, v176 bitop3:0xde
	v_lshlrev_b32_e32 v172, 6, v172
	v_add3_u32 v128, v128, v178, v172
	v_lshl_add_u64 v[172:173], s[28:29], 0, v[128:129]
	v_lshl_add_u64 v[174:175], s[24:25], 0, v[172:173]
	v_lshl_add_u64 v[174:175], v[174:175], 0, s[22:23]
	s_mov_b32 m0, s45
	v_lshl_add_u64 v[172:173], s[26:27], 0, v[172:173]
	v_readfirstlane_b32 s45, v134
	v_add_u32_e32 v128, 0x2000, v171
	global_load_lds_dwordx4 v[174:175], off
	v_lshl_add_u64 v[172:173], v[172:173], 0, s[22:23]
	s_mov_b32 m0, s45
	v_ashrrev_i32_e32 v128, 10, v128
	global_load_lds_dwordx4 v[172:173], off
	v_lshrrev_b32_e32 v172, 31, v128
	v_add_u32_e32 v172, v128, v172
	v_lshrrev_b32_e32 v172, 1, v172
	v_mul_lo_u32 v172, v172, s36
	v_bitop3_b32 v172, v177, v172, v176 bitop3:0xde
	v_lshlrev_b32_e32 v128, 6, v128
	v_add3_u32 v128, v172, v178, v128
	v_lshl_add_u64 v[172:173], s[28:29], 0, v[128:129]
	v_lshl_add_u64 v[174:175], s[24:25], 0, v[172:173]
	v_readfirstlane_b32 s45, v135
	v_lshl_add_u64 v[174:175], v[174:175], 0, s[22:23]
	s_mov_b32 m0, s45
	v_lshl_add_u64 v[172:173], s[26:27], 0, v[172:173]
	v_readfirstlane_b32 s45, v136
	v_add_u32_e32 v128, 0x4000, v171
	global_load_lds_dwordx4 v[174:175], off
	v_lshl_add_u64 v[172:173], v[172:173], 0, s[22:23]
	s_mov_b32 m0, s45
	v_ashrrev_i32_e32 v128, 10, v128
	global_load_lds_dwordx4 v[172:173], off
	v_lshrrev_b32_e32 v172, 31, v128
	v_add_u32_e32 v172, v128, v172
	v_lshrrev_b32_e32 v172, 1, v172
	v_mul_lo_u32 v172, v172, s36
	v_bitop3_b32 v172, v177, v172, v176 bitop3:0xde
	v_lshlrev_b32_e32 v128, 6, v128
	v_add3_u32 v128, v172, v178, v128
	v_lshl_add_u64 v[172:173], s[28:29], 0, v[128:129]
	v_add_u32_e32 v128, 0x6000, v171
	v_ashrrev_i32_e32 v128, 10, v128
	v_lshrrev_b32_e32 v171, 31, v128
	v_add_u32_e32 v171, v128, v171
	v_lshrrev_b32_e32 v171, 1, v171
	v_lshl_add_u64 v[174:175], s[24:25], 0, v[172:173]
	v_readfirstlane_b32 s45, v137
	v_mul_lo_u32 v171, v171, s36
	v_lshl_add_u64 v[174:175], v[174:175], 0, s[22:23]
	s_mov_b32 m0, s45
	v_lshl_add_u64 v[172:173], s[26:27], 0, v[172:173]
	v_readfirstlane_b32 s45, v138
	v_bitop3_b32 v171, v177, v171, v176 bitop3:0xde
	v_lshlrev_b32_e32 v128, 6, v128
	global_load_lds_dwordx4 v[174:175], off
	v_lshl_add_u64 v[172:173], v[172:173], 0, s[22:23]
	s_mov_b32 m0, s45
	v_add3_u32 v128, v171, v178, v128
	global_load_lds_dwordx4 v[172:173], off
	v_lshl_add_u64 v[172:173], s[28:29], 0, v[128:129]
	v_lshl_add_u64 v[174:175], s[24:25], 0, v[172:173]
	v_readfirstlane_b32 s45, v139
	v_lshl_add_u64 v[174:175], v[174:175], 0, s[22:23]
	s_mov_b32 m0, s45
	v_lshl_add_u64 v[172:173], s[26:27], 0, v[172:173]
	v_readfirstlane_b32 s45, v140
	global_load_lds_dwordx4 v[174:175], off
	v_lshl_add_u64 v[172:173], v[172:173], 0, s[22:23]
	s_mov_b32 m0, s45
	s_nop 0
	global_load_lds_dwordx4 v[172:173], off
	s_branch .LBB0_1787

	.amdhsa_kernel _Z14fwd_megakernel6Params
		.amdhsa_group_segment_fixed_size 133140
		.amdhsa_private_segment_fixed_size 0
		.amdhsa_kernarg_size 736
		.amdhsa_user_sgpr_count 2
		.amdhsa_user_sgpr_dispatch_ptr 0
		.amdhsa_user_sgpr_queue_ptr 0
		.amdhsa_user_sgpr_kernarg_segment_ptr 1
		.amdhsa_user_sgpr_dispatch_id 0
		.amdhsa_user_sgpr_kernarg_preload_length 0
		.amdhsa_user_sgpr_kernarg_preload_offset 0
		.amdhsa_user_sgpr_private_segment_size 0
		.amdhsa_uses_dynamic_stack 0
		.amdhsa_enable_private_segment 0
		.amdhsa_system_sgpr_workgroup_id_x 1
		.amdhsa_system_sgpr_workgroup_id_y 0
		.amdhsa_system_sgpr_workgroup_id_z 0
		.amdhsa_system_sgpr_workgroup_info 0
		.amdhsa_system_vgpr_workitem_id 2
		.amdhsa_next_free_vgpr 256
		.amdhsa_next_free_sgpr 102
		.amdhsa_accum_offset 256
		.amdhsa_reserve_vcc 1
		.amdhsa_float_round_mode_32 0
		.amdhsa_float_round_mode_16_64 0
		.amdhsa_float_denorm_mode_32 3
		.amdhsa_float_denorm_mode_16_64 3
		.amdhsa_dx10_clamp 1
		.amdhsa_ieee_mode 1
		.amdhsa_fp16_overflow 0
		.amdhsa_tg_split 0
		.amdhsa_exception_fp_ieee_invalid_op 0
		.amdhsa_exception_fp_denorm_src 0
		.amdhsa_exception_fp_ieee_div_zero 0
		.amdhsa_exception_fp_ieee_overflow 0
		.amdhsa_exception_fp_ieee_underflow 0
		.amdhsa_exception_fp_ieee_inexact 0
		.amdhsa_exception_int_div_zero 0
	.end_amdhsa_kernel

amdhsa.kernels:
  - .agpr_count:     0
    .args:
      - .offset:         0
        .size:           480
        .value_kind:     by_value
      - .offset:         480
        .size:           4
        .value_kind:     hidden_block_count_x
      - .offset:         484
        .size:           4
        .value_kind:     hidden_block_count_y
      - .offset:         488
        .size:           4
        .value_kind:     hidden_block_count_z
      - .offset:         492
        .size:           2
        .value_kind:     hidden_group_size_x
      - .offset:         494
        .size:           2
        .value_kind:     hidden_group_size_y
      - .offset:         496
        .size:           2
        .value_kind:     hidden_group_size_z
      - .offset:         498
        .size:           2
        .value_kind:     hidden_remainder_x
      - .offset:         500
        .size:           2
        .value_kind:     hidden_remainder_y
      - .offset:         502
        .size:           2
        .value_kind:     hidden_remainder_z
      - .offset:         520
        .size:           8
        .value_kind:     hidden_global_offset_x
      - .offset:         528
        .size:           8
        .value_kind:     hidden_global_offset_y
      - .offset:         536
        .size:           8
        .value_kind:     hidden_global_offset_z
      - .offset:         544
        .size:           2
        .value_kind:     hidden_grid_dims
      - .offset:         568
        .size:           8
        .value_kind:     hidden_multigrid_sync_arg
    .group_segment_fixed_size: 133140
    .kernarg_segment_align: 8
    .kernarg_segment_size: 736
    .language:       OpenCL C
    .language_version:
      - 2
      - 0
    .max_flat_workgroup_size: 512
    .name:           _Z14fwd_megakernel6Params
    .private_segment_fixed_size: 0
    .sgpr_count:     108
    .sgpr_spill_count: 175
    .symbol:         _Z14fwd_megakernel6Params.kd
    .uniform_work_group_size: 1
    .uses_dynamic_stack: false
    .vgpr_count:     256
    .vgpr_spill_count: 0
    .wavefront_size: 64
